# non-temporal (nt) policy on once-read streams: row-phase residual loads, initial-norm input loads, prologue weight loads (touch prefetch dropped)
# speedup vs baseline: 1.0131x; 1.0108x over previous
; __device__ __forceinline__ f32x4 bfx4_lo(u32x4 w) { return (f32x4){bf_lo(w.x), bf_hi(w.x), bf_lo(w.y), bf_hi(w.y)}; }
; __device__ __forceinline__ f32x4 bfx4_hi(u32x4 w) { return (f32x4){bf_lo(w.z), bf_hi(w.z), bf_lo(w.w), bf_hi(w.w)}; }
; __device__ __forceinline__ void phase_rows(const Params& p, const RowArgs& a, int G, int wave, int lane) {
;     ...
;     for (int it = (a.ctx_only && bmaj) ? ppw : 0; it < nit; ++it) {
;         int mp;
;         if (bmaj) mp = (it < ppw) ? (gw / wpb) * (SEQ / 2) + (gw % wpb) + it * wpb : ML / 2 + gw + (it - ppw) * NGW;
;         else mp = ((a.ctx_only && !bmaj) ? ML / 2 : 0) + gw + it * NGW;
;         if (mp >= a.nrows / 2) break;
;         const int m0 = 2 * mp; const bool isl = m0 < ML; const int rb = isl ? (m0 >> 12) : 8;
;         const bool use_y = a.has_y && !(a.lat_no_y && isl);
;         const size_t xoff = isl ? (size_t)m0 * DM : (size_t)(m0 - ML) * DM;
;         const void* xrb = isl ? a.xlat : a.xctx; void* xob = isl ? a.olat : a.octx;
;         bf16_t* xn = XN + (size_t)m0 * DM;
;         const size_t moff = (size_t)rb * NMOD;
;         f32x4 v[2][4], y[2][4];
;         if (a.xin_f32) {
; #pragma unroll
;             for (int u = 0; u < 2; ++u)
; #pragma unroll
;                 for (int j = 0; j < 4; ++j) v[u][j] = *(const f32x4*)((const float*)xrb + xoff + u * DM + 8 * lane + 512 * (j >> 1) + 4 * (j & 1));
;         } else {
; #pragma unroll
;             for (int u = 0; u < 2; ++u)
; #pragma unroll
;                 for (int jb = 0; jb < 2; ++jb) { const u32x4 xw = *(const u32x4*)((const bf16_t*)xrb + xoff + u * DM + 8 * lane + 512 * jb); v[u][2 * jb] = bfx4_lo(xw); v[u][2 * jb + 1] = bfx4_hi(xw); }
;         }
;     ...
;             if (a.write_xn) {
; #pragma unroll
;                 for (int j = 0; j < 4; ++j) { const int c = 8 * lane + 512 * (j >> 1) + 4 * (j & 1); sh[j] = *(const f32x4*)(a.mod_nxt + moff + a.sh_off + c); sc[j] = *(const f32x4*)(a.mod_nxt + moff + a.sc_off + c); }
;             }
.LBB0_29:
	s_cmpk_gt_i32 s6, 0x43ff
	s_mov_b64 s[0:1], -1
	s_cbranch_scc1 .LBB0_23
	s_lshl_b32 s0, s6, 1
	s_min_i32 s1, s6, 0x4000
	s_ashr_i32 s17, s1, 11
	s_ashr_i32 s1, s0, 31
	s_add_i32 s18, s0, 0xffff8000
	s_cmpk_lt_i32 s6, 0x4000
	s_cselect_b64 s[6:7], -1, 0
	s_and_b64 s[8:9], s[6:7], exec
	v_readlane_b32 s36, v254, 42
	s_cselect_b32 s19, s1, 0
	s_cselect_b32 s18, s0, s18
	v_readlane_b32 s37, v254, 43
	v_readlane_b32 s40, v254, 46
	v_readlane_b32 s41, v254, 47
	s_cselect_b32 s20, s37, s41
	s_cselect_b32 s21, s36, s40
	s_lshl_b64 s[8:9], s[18:19], 10
	s_add_u32 s21, s21, s92
	s_addc_u32 s20, s20, s93
	s_lshl_b64 s[18:19], s[18:19], 12
	s_add_u32 s18, s21, s18
	s_addc_u32 s19, s20, s19
	v_lshlrev_b32_e32 v156, 2, v84
	v_lshl_add_u64 v[48:49], s[18:19], 0, v[156:157]
	global_load_dwordx4 v[72:75], v156, s[18:19] offset:16 nt
	global_load_dwordx4 v[76:79], v156, s[18:19] nt
	global_load_dwordx4 v[64:67], v156, s[18:19] offset:2064 nt
	global_load_dwordx4 v[68:71], v156, s[18:19] offset:2048 nt
	s_mov_b64 s[18:19], 0x1000
	v_lshl_add_u64 v[50:51], v[48:49], 0, s[18:19]
	v_add_co_u32_e32 v52, vcc, 0x1000, v48
	s_mov_b64 s[18:19], 0x1800
	s_nop 0
	v_addc_co_u32_e32 v53, vcc, 0, v49, vcc
	v_lshl_add_u64 v[48:49], v[48:49], 0, s[18:19]
	global_load_dwordx4 v[60:63], v[52:53], off nt
	global_load_dwordx4 v[56:59], v[50:51], off offset:16 nt
	s_nop 0
	global_load_dwordx4 v[52:55], v[52:53], off offset:2048 nt
	s_nop 0
	global_load_dwordx4 v[48:51], v[48:49], off offset:16 nt
	s_cmp_eq_u32 s17, s16
	v_readlane_b32 s38, v254, 44
	v_readlane_b32 s39, v254, 45
	v_readlane_b32 s42, v254, 48
	v_readlane_b32 s43, v254, 49
	v_readlane_b32 s44, v254, 50
	v_readlane_b32 s45, v254, 51
	v_readlane_b32 s46, v254, 52
	v_readlane_b32 s47, v254, 53
	v_readlane_b32 s48, v254, 54
	v_readlane_b32 s49, v254, 55
	v_readlane_b32 s50, v254, 56
	v_readlane_b32 s51, v254, 57
	s_cbranch_scc1 .LBB0_22
	s_mul_i32 s18, s17, 0x6000
	s_mul_hi_i32 s16, s17, 0x6000
	s_add_u32 s18, s73, s18
	s_addc_u32 s19, s57, s16
	s_add_u32 s20, s18, 0x1000
	s_addc_u32 s21, s19, 0
	global_load_dwordx4 v[20:23], v156, s[18:19] offset:16
	global_load_dwordx4 v[16:19], v156, s[18:19]
	global_load_dwordx4 v[24:27], v156, s[20:21] offset:16
	global_load_dwordx4 v[28:31], v156, s[20:21]
	global_load_dwordx4 v[32:35], v156, s[18:19] offset:2064
	global_load_dwordx4 v[36:39], v156, s[18:19] offset:2048
	global_load_dwordx4 v[40:43], v81, s[20:21] offset:16
	global_load_dwordx4 v[44:47], v81, s[20:21]
	s_mov_b32 s16, s17
	s_branch .LBB0_22

; __device__ __forceinline__ f32x4 bfx4_lo(u32x4 w) { return (f32x4){bf_lo(w.x), bf_hi(w.x), bf_lo(w.y), bf_hi(w.y)}; }
; __device__ __forceinline__ void phase_rows(const Params& p, const RowArgs& a, int G, int wave, int lane) {
;     ...
;         if (bmaj) mp = (it < ppw) ? (gw / wpb) * (SEQ / 2) + (gw % wpb) + it * wpb : ML / 2 + gw + (it - ppw) * NGW;
;         else mp = ((a.ctx_only && !bmaj) ? ML / 2 : 0) + gw + it * NGW;
;         if (mp >= a.nrows / 2) break;
;         const int m0 = 2 * mp; const bool isl = m0 < ML; const int rb = isl ? (m0 >> 12) : 8;
;         const bool use_y = a.has_y && !(a.lat_no_y && isl);
;         const size_t xoff = isl ? (size_t)m0 * DM : (size_t)(m0 - ML) * DM;
;         const void* xrb = isl ? a.xlat : a.xctx; void* xob = isl ? a.olat : a.octx;
;         bf16_t* xn = XN + (size_t)m0 * DM;
;         const size_t moff = (size_t)rb * NMOD;
;         f32x4 v[2][4], y[2][4];
;         if (a.xin_f32) {
; #pragma unroll
;             for (int u = 0; u < 2; ++u)
; #pragma unroll
;                 for (int j = 0; j < 4; ++j) v[u][j] = *(const f32x4*)((const float*)xrb + xoff + u * DM + 8 * lane + 512 * (j >> 1) + 4 * (j & 1));
;         } else {
; #pragma unroll
;             for (int u = 0; u < 2; ++u)
; #pragma unroll
;                 for (int jb = 0; jb < 2; ++jb) { const u32x4 xw = *(const u32x4*)((const bf16_t*)xrb + xoff + u * DM + 8 * lane + 512 * jb); v[u][2 * jb] = bfx4_lo(xw); v[u][2 * jb + 1] = bfx4_hi(xw); }
;         }
;         if (use_y) {
;             if (isl || !a.ctx_split) {
; #pragma unroll
;                 for (int u = 0; u < 2; ++u)
; #pragma unroll
;                     for (int jb = 0; jb < 2; ++jb) { const u32x4 yw = *(const u32x4*)(xn + u * DM + 8 * lane + 512 * jb); y[u][2 * jb] = bfx4_lo(yw); y[u][2 * jb + 1] = bfx4_hi(yw); }
;             } else {
;                 const float* part = (const float*)p.out;
; #pragma unroll
;                 for (int u = 0; u < 2; ++u)
; #pragma unroll
;                     for (int j = 0; j < 4; ++j) { const float* pp = part + (size_t)(m0 + u - ML) * DM + 8 * lane + 512 * (j >> 1) + 4 * (j & 1); f32x4 s = *(const f32x4*)pp;
; #pragma unroll
;                         for (int k = 1; k < pg8::KSPLIT; ++k) s += *(const f32x4*)(pp + (size_t)k * MC * DM);
;                         y[u][j] = s; }
;             }
.LBB0_210:
	s_cmp_ge_i32 s11, s19
	s_mov_b64 s[0:1], -1
	s_cbranch_scc1 .LBB0_204
	s_lshl_b32 s4, s11, 1
	s_cmpk_lt_i32 s11, 0x4000
	s_cselect_b64 s[0:1], -1, 0
	s_ashr_i32 s5, s4, 31
	s_add_i32 s30, s4, 0xffff8000
	s_cmpk_gt_i32 s11, 0x3fff
	s_cselect_b64 s[8:9], -1, 0
	s_and_b64 s[6:7], s[8:9], exec
	s_cselect_b32 s7, 0, s5
	s_cselect_b32 s6, s30, s4
	s_cselect_b32 s23, s99, s79
	s_cselect_b32 s26, s98, s78
	s_lshl_b64 s[24:25], s[6:7], 11
	s_add_u32 s24, s26, s24
	s_addc_u32 s25, s23, s25
	global_load_dwordx4 v[116:119], v170, s[24:25] nt
	global_load_dwordx4 v[112:115], v170, s[24:25] offset:1024 nt
	global_load_dwordx4 v[108:111], v170, s[24:25] offset:2048 nt
	global_load_dwordx4 v[104:107], v170, s[24:25] offset:3072 nt
	v_lshl_add_u64 v[248:249], s[24:25], 0, v[250:251]
	s_add_i32 s32, s11, s52
	s_cmpk_lt_i32 s32, 0x4000
	s_cselect_b32 s32, 1, 0
	s_and_b32 s32, s32, s82
	s_and_b64 vcc, exec, s[0:1]
	s_cbranch_vccnz .LBB0_213
	s_lshl_b64 s[24:25], s[30:31], 12
	v_lshl_add_u64 v[88:89], v[176:177], 0, s[24:25]
	v_add_co_u32_e32 v96, vcc, 0x800000, v88
	global_load_dwordx4 v[84:87], v[88:89], off offset:16
	global_load_dwordx4 v[80:83], v[88:89], off
	s_mov_b64 s[26:27], 0x800000
	v_addc_co_u32_e32 v97, vcc, 0, v89, vcc
	v_lshl_add_u64 v[94:95], v[88:89], 0, s[26:27]
	global_load_dwordx4 v[90:93], v[96:97], off
	global_load_dwordx4 v[126:129], v[94:95], off offset:16
	s_mov_b64 s[28:29], 0x1000000
	v_add_co_u32_e32 v122, vcc, 0x1000000, v88
	s_mov_b64 s[62:63], 0x1800000
	s_nop 0
	v_addc_co_u32_e32 v123, vcc, 0, v89, vcc
	v_add_co_u32_e32 v120, vcc, 0x1800000, v88
	v_lshl_add_u64 v[100:101], v[88:89], 0, s[62:63]
	s_nop 0
	v_addc_co_u32_e32 v121, vcc, 0, v89, vcc
	v_add_co_u32_e32 v102, vcc, 0x2000000, v88
	s_mov_b64 s[64:65], 0x2000000
	s_nop 0
	v_addc_co_u32_e32 v103, vcc, 0, v89, vcc
	v_add_co_u32_e32 v124, vcc, 0x2800000, v88
	s_mov_b64 s[68:69], 0x2800000
	s_nop 0
	v_addc_co_u32_e32 v125, vcc, 0, v89, vcc
	s_mov_b64 s[70:71], 0x3000000
	v_lshl_add_u64 v[142:143], v[88:89], 0, s[70:71]
	s_mov_b64 s[74:75], 0x3800000
	v_lshl_add_u64 v[146:147], v[88:89], 0, s[74:75]
	s_mov_b64 s[76:77], 0x800800
	s_mov_b64 s[40:41], s[34:35]
	s_mov_b64 s[34:35], 0x1000800
	s_mov_b64 s[86:87], 0x1800800
	s_mov_b64 s[94:95], 0x2000800
	s_mov_b64 s[14:15], 0x2800800
	s_mov_b32 s33, s96
	s_mov_b32 s39, s97
	s_mov_b64 s[96:97], 0x3000800
	s_mov_b64 s[36:37], 0x3800800
	s_add_i32 s30, s4, 0xffff8001
	s_lshl_b64 s[24:25], s[30:31], 12
	s_mov_b32 s23, 0x1000000
	s_waitcnt vmcnt(0)
	v_pk_add_f32 v[98:99], v[82:83], v[92:93]
	v_lshl_add_u64 v[92:93], v[88:89], 0, s[28:29]
	v_pk_add_f32 v[90:91], v[80:81], v[90:91]
	global_load_dwordx4 v[80:83], v[122:123], off
	s_nop 0
	global_load_dwordx4 v[92:95], v[92:93], off offset:16
	v_pk_add_f32 v[86:87], v[86:87], v[128:129]
	v_pk_add_f32 v[84:85], v[84:85], v[126:127]
	s_waitcnt vmcnt(1)
	v_pk_add_f32 v[98:99], v[98:99], v[82:83]
	v_pk_add_f32 v[90:91], v[90:91], v[80:81]
	global_load_dwordx4 v[80:83], v[120:121], off
	global_load_dwordx4 v[130:133], v[100:101], off offset:16
	v_lshl_add_u64 v[100:101], v[88:89], 0, s[64:65]
	s_waitcnt vmcnt(2)
	v_pk_add_f32 v[86:87], v[86:87], v[94:95]
	v_pk_add_f32 v[84:85], v[84:85], v[92:93]
	s_waitcnt vmcnt(1)
	v_pk_add_f32 v[98:99], v[98:99], v[82:83]
	v_pk_add_f32 v[90:91], v[90:91], v[80:81]
	global_load_dwordx4 v[80:83], v[102:103], off
	global_load_dwordx4 v[134:137], v[100:101], off offset:16
	v_lshl_add_u64 v[100:101], v[88:89], 0, s[68:69]
	s_waitcnt vmcnt(2)
	v_pk_add_f32 v[86:87], v[86:87], v[132:133]
	v_pk_add_f32 v[84:85], v[84:85], v[130:131]
	s_waitcnt vmcnt(1)
	v_pk_add_f32 v[98:99], v[98:99], v[82:83]
	v_pk_add_f32 v[90:91], v[90:91], v[80:81]
	global_load_dwordx4 v[80:83], v[124:125], off
	global_load_dwordx4 v[138:141], v[100:101], off offset:16
	v_add_co_u32_e32 v100, vcc, 0x3000000, v88
	s_waitcnt vmcnt(2)
	v_pk_add_f32 v[86:87], v[86:87], v[136:137]
	v_addc_co_u32_e32 v101, vcc, 0, v89, vcc
	v_pk_add_f32 v[84:85], v[84:85], v[134:135]
	s_waitcnt vmcnt(1)
	v_pk_add_f32 v[98:99], v[98:99], v[82:83]
	v_pk_add_f32 v[90:91], v[90:91], v[80:81]
	global_load_dwordx4 v[80:83], v[100:101], off
	s_nop 0
	global_load_dwordx4 v[142:145], v[142:143], off offset:16
	s_waitcnt vmcnt(2)
	v_pk_add_f32 v[84:85], v[84:85], v[138:139]
	v_pk_add_f32 v[86:87], v[86:87], v[140:141]
	s_waitcnt vmcnt(1)
	v_pk_add_f32 v[150:151], v[90:91], v[80:81]
	v_add_co_u32_e32 v90, vcc, 0x3800000, v88
	v_pk_add_f32 v[98:99], v[98:99], v[82:83]
	s_nop 0
	v_addc_co_u32_e32 v91, vcc, 0, v89, vcc
	global_load_dwordx4 v[80:83], v[90:91], off
	s_nop 0
	global_load_dwordx4 v[146:149], v[146:147], off offset:16
	s_nop 0
	global_load_dwordx4 v[92:95], v[88:89], off offset:2064
	global_load_dwordx4 v[126:129], v[88:89], off offset:2048
	s_waitcnt vmcnt(4)
	v_pk_add_f32 v[84:85], v[84:85], v[142:143]
	v_pk_add_f32 v[86:87], v[86:87], v[144:145]
	s_waitcnt vmcnt(3)
	v_pk_add_f32 v[82:83], v[98:99], v[82:83]
	v_lshl_add_u64 v[98:99], v[88:89], 0, s[76:77]
	global_load_dwordx4 v[130:133], v[96:97], off offset:2048
	s_nop 0
	global_load_dwordx4 v[96:99], v[98:99], off offset:16
	s_waitcnt vmcnt(4)
	v_pk_add_f32 v[86:87], v[86:87], v[148:149]
	v_pk_add_f32 v[84:85], v[84:85], v[146:147]
	v_pk_add_f32 v[80:81], v[150:151], v[80:81]
	s_waitcnt vmcnt(1)
	v_pk_add_f32 v[136:137], v[126:127], v[130:131]
	v_lshl_add_u64 v[130:131], v[88:89], 0, s[34:35]
	v_pk_add_f32 v[134:135], v[128:129], v[132:133]
	global_load_dwordx4 v[126:129], v[122:123], off offset:2048
	s_nop 0
	global_load_dwordx4 v[130:133], v[130:131], off offset:16
	s_waitcnt vmcnt(2)
	v_pk_add_f32 v[92:93], v[92:93], v[96:97]
	v_pk_add_f32 v[94:95], v[94:95], v[98:99]
	s_waitcnt vmcnt(1)
; __device__ __forceinline__ void phase_rows(const Params& p, const RowArgs& a, int G, int wave, int lane) {
;     ...
;                 const float* part = (const float*)p.out;
; #pragma unroll
;                 for (int u = 0; u < 2; ++u)
; #pragma unroll
;                     for (int j = 0; j < 4; ++j) { const float* pp = part + (size_t)(m0 + u - ML) * DM + 8 * lane + 512 * (j >> 1) + 4 * (j & 1); f32x4 s = *(const f32x4*)pp;
; #pragma unroll
;                         for (int k = 1; k < pg8::KSPLIT; ++k) s += *(const f32x4*)(pp + (size_t)k * MC * DM);
;                         y[u][j] = s; }
;             }
	v_pk_add_f32 v[136:137], v[136:137], v[126:127]
	v_lshl_add_u64 v[126:127], v[88:89], 0, s[86:87]
	v_pk_add_f32 v[134:135], v[134:135], v[128:129]
	global_load_dwordx4 v[120:123], v[120:121], off offset:2048
	s_nop 0
	global_load_dwordx4 v[126:129], v[126:127], off offset:16
	s_waitcnt vmcnt(2)
	v_pk_add_f32 v[92:93], v[92:93], v[130:131]
	v_pk_add_f32 v[94:95], v[94:95], v[132:133]
	s_waitcnt vmcnt(1)
	v_pk_add_f32 v[138:139], v[134:135], v[122:123]
	v_lshl_add_u64 v[134:135], v[88:89], 0, s[94:95]
	v_pk_add_f32 v[140:141], v[136:137], v[120:121]
	global_load_dwordx4 v[120:123], v[102:103], off offset:2048
	s_nop 0
	global_load_dwordx4 v[134:137], v[134:135], off offset:16
	s_waitcnt vmcnt(2)
	v_pk_add_f32 v[92:93], v[92:93], v[126:127]
	v_pk_add_f32 v[94:95], v[94:95], v[128:129]
	s_waitcnt vmcnt(1)
	v_pk_add_f32 v[102:103], v[138:139], v[122:123]
	v_lshl_add_u64 v[138:139], v[88:89], 0, s[14:15]
	v_pk_add_f32 v[142:143], v[140:141], v[120:121]
	global_load_dwordx4 v[120:123], v[124:125], off offset:2048
	s_nop 0
	global_load_dwordx4 v[138:141], v[138:139], off offset:16
	s_waitcnt vmcnt(2)
	v_pk_add_f32 v[92:93], v[92:93], v[134:135]
	v_pk_add_f32 v[94:95], v[94:95], v[136:137]
	s_waitcnt vmcnt(1)
	v_pk_add_f32 v[142:143], v[142:143], v[120:121]
	v_lshl_add_u64 v[120:121], v[88:89], 0, s[96:97]
	v_pk_add_f32 v[124:125], v[102:103], v[122:123]
	global_load_dwordx4 v[100:103], v[100:101], off offset:2048
	s_nop 0
	global_load_dwordx4 v[120:123], v[120:121], off offset:16
	s_waitcnt vmcnt(2)
	v_pk_add_f32 v[92:93], v[92:93], v[138:139]
	v_pk_add_f32 v[94:95], v[94:95], v[140:141]
	s_waitcnt vmcnt(1)
	v_pk_add_f32 v[142:143], v[142:143], v[100:101]
	v_lshl_add_u64 v[100:101], v[88:89], 0, s[36:37]
	v_pk_add_f32 v[124:125], v[124:125], v[102:103]
	global_load_dwordx4 v[88:91], v[90:91], off offset:2048
	s_nop 0
	global_load_dwordx4 v[100:103], v[100:101], off offset:16
	s_waitcnt vmcnt(2)
	v_pk_add_f32 v[92:93], v[92:93], v[120:121]
	v_lshl_add_u64 v[120:121], v[176:177], 0, s[24:25]
	v_pk_add_f32 v[94:95], v[94:95], v[122:123]
	v_add_co_u32_e32 v128, vcc, s55, v120
	v_lshl_add_u64 v[126:127], v[120:121], 0, s[26:27]
	s_nop 0
	v_addc_co_u32_e32 v129, vcc, 0, v121, vcc
	v_add_co_u32_e32 v132, vcc, s23, v120
	s_mov_b32 s23, 0x1800000
	s_nop 0
	v_addc_co_u32_e32 v133, vcc, 0, v121, vcc
	v_add_co_u32_e32 v136, vcc, s23, v120
	v_lshl_add_u64 v[134:135], v[120:121], 0, s[62:63]
	s_nop 0
	v_addc_co_u32_e32 v137, vcc, 0, v121, vcc
	s_brev_b32 s23, 64
	s_waitcnt vmcnt(1)
	v_pk_add_f32 v[90:91], v[124:125], v[90:91]
	s_waitcnt vmcnt(0)
	v_pk_add_f32 v[94:95], v[94:95], v[102:103]
	v_pk_add_f32 v[92:93], v[92:93], v[100:101]
	global_load_dwordx4 v[100:103], v[120:121], off offset:16
	global_load_dwordx4 v[96:99], v[120:121], off
	global_load_dwordx4 v[122:125], v[128:129], off
	global_load_dwordx4 v[138:141], v[126:127], off offset:16
	v_pk_add_f32 v[88:89], v[142:143], v[88:89]
	v_lshl_add_u64 v[142:143], v[120:121], 0, s[64:65]
	s_waitcnt vmcnt(1)
	v_pk_add_f32 v[130:131], v[98:99], v[124:125]
	v_lshl_add_u64 v[124:125], v[120:121], 0, s[28:29]
	v_pk_add_f32 v[122:123], v[96:97], v[122:123]
	global_load_dwordx4 v[96:99], v[132:133], off
	s_nop 0
	global_load_dwordx4 v[124:127], v[124:125], off offset:16
	s_waitcnt vmcnt(2)
	v_pk_add_f32 v[102:103], v[102:103], v[140:141]
	v_pk_add_f32 v[100:101], v[100:101], v[138:139]
	s_waitcnt vmcnt(1)
	v_pk_add_f32 v[130:131], v[130:131], v[98:99]
	v_pk_add_f32 v[122:123], v[122:123], v[96:97]
	global_load_dwordx4 v[96:99], v[136:137], off
	global_load_dwordx4 v[178:181], v[134:135], off offset:16
	s_waitcnt vmcnt(2)
	v_pk_add_f32 v[102:103], v[102:103], v[126:127]
	v_pk_add_f32 v[100:101], v[100:101], v[124:125]
	s_waitcnt vmcnt(1)
	v_pk_add_f32 v[134:135], v[122:123], v[96:97]
	v_add_co_u32_e32 v122, vcc, s23, v120
	v_pk_add_f32 v[130:131], v[130:131], v[98:99]
	s_nop 0
	v_addc_co_u32_e32 v123, vcc, 0, v121, vcc
	global_load_dwordx4 v[96:99], v[122:123], off
	global_load_dwordx4 v[182:185], v[142:143], off offset:16
	s_mov_b32 s23, 0x2800000
	v_add_co_u32_e32 v144, vcc, s23, v120
	v_lshl_add_u64 v[142:143], v[120:121], 0, s[68:69]
	s_nop 0
	v_addc_co_u32_e32 v145, vcc, 0, v121, vcc
	s_mov_b32 s23, 0x3000000
	v_add_co_u32_e32 v148, vcc, s23, v120
	s_mov_b32 s23, 0x3800000
	s_nop 0
	v_addc_co_u32_e32 v149, vcc, 0, v121, vcc
	v_add_co_u32_e32 v152, vcc, s23, v120
	s_waitcnt vmcnt(2)
	v_pk_add_f32 v[102:103], v[102:103], v[180:181]
	v_addc_co_u32_e32 v153, vcc, 0, v121, vcc
	v_pk_add_f32 v[100:101], v[100:101], v[178:179]
	s_waitcnt vmcnt(1)
; __device__ __forceinline__ void phase_rows(const Params& p, const RowArgs& a, int G, int wave, int lane) {
;     ...
;                 const float* part = (const float*)p.out;
; #pragma unroll
;                 for (int u = 0; u < 2; ++u)
; #pragma unroll
;                     for (int j = 0; j < 4; ++j) { const float* pp = part + (size_t)(m0 + u - ML) * DM + 8 * lane + 512 * (j >> 1) + 4 * (j & 1); f32x4 s = *(const f32x4*)pp;
; #pragma unroll
;                         for (int k = 1; k < pg8::KSPLIT; ++k) s += *(const f32x4*)(pp + (size_t)k * MC * DM);
;                         y[u][j] = s; }
;             }
	v_pk_add_f32 v[130:131], v[130:131], v[98:99]
	v_pk_add_f32 v[134:135], v[134:135], v[96:97]
	global_load_dwordx4 v[96:99], v[144:145], off
	global_load_dwordx4 v[186:189], v[142:143], off offset:16
	v_lshl_add_u64 v[142:143], v[120:121], 0, s[70:71]
	s_waitcnt vmcnt(2)
	v_pk_add_f32 v[100:101], v[100:101], v[182:183]
	v_pk_add_f32 v[102:103], v[102:103], v[184:185]
	s_waitcnt vmcnt(1)
	v_pk_add_f32 v[130:131], v[130:131], v[98:99]
	v_pk_add_f32 v[134:135], v[134:135], v[96:97]
	global_load_dwordx4 v[96:99], v[148:149], off
	global_load_dwordx4 v[190:193], v[142:143], off offset:16
	v_lshl_add_u64 v[142:143], v[120:121], 0, s[74:75]
	s_waitcnt vmcnt(2)
	v_pk_add_f32 v[102:103], v[102:103], v[188:189]
	v_pk_add_f32 v[100:101], v[100:101], v[186:187]
	s_waitcnt vmcnt(1)
	v_pk_add_f32 v[130:131], v[130:131], v[98:99]
	v_pk_add_f32 v[134:135], v[134:135], v[96:97]
	global_load_dwordx4 v[96:99], v[152:153], off
	global_load_dwordx4 v[194:197], v[142:143], off offset:16
	global_load_dwordx4 v[124:127], v[120:121], off offset:2064
	global_load_dwordx4 v[138:141], v[120:121], off offset:2048
	s_waitcnt vmcnt(4)
	v_pk_add_f32 v[102:103], v[102:103], v[192:193]
	v_pk_add_f32 v[100:101], v[100:101], v[190:191]
	s_waitcnt vmcnt(3)
	v_pk_add_f32 v[98:99], v[130:131], v[98:99]
	v_lshl_add_u64 v[130:131], v[120:121], 0, s[76:77]
	global_load_dwordx4 v[178:181], v[128:129], off offset:2048
	s_nop 0
	global_load_dwordx4 v[128:131], v[130:131], off offset:16
	v_pk_add_f32 v[96:97], v[134:135], v[96:97]
	v_lshl_add_u64 v[134:135], v[120:121], 0, s[34:35]
	s_waitcnt vmcnt(4)
	v_pk_add_f32 v[102:103], v[102:103], v[196:197]
	v_pk_add_f32 v[100:101], v[100:101], v[194:195]
	s_mov_b64 s[34:35], s[40:41]
	s_waitcnt vmcnt(1)
	v_pk_add_f32 v[142:143], v[140:141], v[180:181]
	v_pk_add_f32 v[146:147], v[138:139], v[178:179]
	global_load_dwordx4 v[138:141], v[132:133], off offset:2048
	s_nop 0
	global_load_dwordx4 v[132:135], v[134:135], off offset:16
	s_waitcnt vmcnt(2)
	v_pk_add_f32 v[126:127], v[126:127], v[130:131]
	v_pk_add_f32 v[124:125], v[124:125], v[128:129]
	s_waitcnt vmcnt(1)
	v_pk_add_f32 v[146:147], v[146:147], v[138:139]
	v_lshl_add_u64 v[138:139], v[120:121], 0, s[86:87]
	v_pk_add_f32 v[150:151], v[142:143], v[140:141]
	global_load_dwordx4 v[140:143], v[136:137], off offset:2048
	s_nop 0
	global_load_dwordx4 v[136:139], v[138:139], off offset:16
	s_waitcnt vmcnt(2)
	v_pk_add_f32 v[126:127], v[126:127], v[134:135]
	v_pk_add_f32 v[124:125], v[124:125], v[132:133]
	s_mov_b32 s87, s38
	v_readlane_b32 s86, v255, 11
	s_waitcnt vmcnt(1)
	v_pk_add_f32 v[146:147], v[146:147], v[140:141]
	v_lshl_add_u64 v[140:141], v[120:121], 0, s[94:95]
	v_pk_add_f32 v[150:151], v[150:151], v[142:143]
	global_load_dwordx4 v[178:181], v[122:123], off offset:2048
	s_nop 0
	global_load_dwordx4 v[140:143], v[140:141], off offset:16
	s_waitcnt vmcnt(2)
	v_pk_add_f32 v[126:127], v[126:127], v[138:139]
	v_pk_add_f32 v[124:125], v[124:125], v[136:137]
	v_readlane_b32 s94, v255, 27
	v_readlane_b32 s95, v255, 28
	s_waitcnt vmcnt(1)
	v_pk_add_f32 v[122:123], v[150:151], v[180:181]
	v_pk_add_f32 v[150:151], v[146:147], v[178:179]
	v_lshl_add_u64 v[146:147], v[120:121], 0, s[14:15]
	global_load_dwordx4 v[178:181], v[144:145], off offset:2048
	s_nop 0
	global_load_dwordx4 v[144:147], v[146:147], off offset:16
	s_waitcnt vmcnt(2)
	v_pk_add_f32 v[126:127], v[126:127], v[142:143]
	v_pk_add_f32 v[124:125], v[124:125], v[140:141]
	s_waitcnt vmcnt(1)
	v_pk_add_f32 v[154:155], v[150:151], v[178:179]
	v_lshl_add_u64 v[150:151], v[120:121], 0, s[96:97]
	v_pk_add_f32 v[122:123], v[122:123], v[180:181]
	global_load_dwordx4 v[180:183], v[148:149], off offset:2048
	s_nop 0
	global_load_dwordx4 v[148:151], v[150:151], off offset:16
	s_waitcnt vmcnt(2)
	v_pk_add_f32 v[126:127], v[126:127], v[146:147]
	v_pk_add_f32 v[124:125], v[124:125], v[144:145]
	s_mov_b32 s97, s39
	s_mov_b32 s96, s33
	s_waitcnt vmcnt(1)
	v_pk_add_f32 v[180:181], v[154:155], v[180:181]
	v_lshl_add_u64 v[154:155], v[120:121], 0, s[36:37]
	v_pk_add_f32 v[178:179], v[122:123], v[182:183]
	global_load_dwordx4 v[120:123], v[152:153], off offset:2048
	s_nop 0
	global_load_dwordx4 v[152:155], v[154:155], off offset:16
	s_waitcnt vmcnt(2)
	v_pk_add_f32 v[126:127], v[126:127], v[150:151]
	v_pk_add_f32 v[124:125], v[124:125], v[148:149]
	s_waitcnt vmcnt(1)
	v_pk_add_f32 v[122:123], v[178:179], v[122:123]
	v_pk_add_f32 v[120:121], v[180:181], v[120:121]
	s_waitcnt vmcnt(0)
	v_pk_add_f32 v[126:127], v[126:127], v[154:155]
	v_pk_add_f32 v[124:125], v[124:125], v[152:153]

; __device__ __forceinline__ void phase_rows(const Params& p, const RowArgs& a, int G, int wave, int lane) {
;     ...
;         if (use_y) {
;             if (isl || !a.ctx_split) {
; #pragma unroll
;                 for (int u = 0; u < 2; ++u)
; #pragma unroll
;                     for (int jb = 0; jb < 2; ++jb) { const u32x4 yw = *(const u32x4*)(xn + u * DM + 8 * lane + 512 * jb); y[u][2 * jb] = bfx4_lo(yw); y[u][2 * jb + 1] = bfx4_hi(yw); }
;             } else {
;                 const float* part = (const float*)p.out;
; #pragma unroll
;                 for (int u = 0; u < 2; ++u)
; #pragma unroll
;                     for (int j = 0; j < 4; ++j) { const float* pp = part + (size_t)(m0 + u - ML) * DM + 8 * lane + 512 * (j >> 1) + 4 * (j & 1); f32x4 s = *(const f32x4*)pp;
; #pragma unroll
;                         for (int k = 1; k < pg8::KSPLIT; ++k) s += *(const f32x4*)(pp + (size_t)k * MC * DM);
;                         y[u][j] = s; }
;             }
;         }
;         if (rb != cur_rb) {
;             cur_rb = rb;
;             if (use_y) {
; #pragma unroll
;                 for (int j = 0; j < 4; ++j) gt[j] = *(const f32x4*)(a.mod_cur + moff + a.gate_off + 8 * lane + 512 * (j >> 1) + 4 * (j & 1));
;             }
;             if (a.write_xn) {
; #pragma unroll
;                 for (int j = 0; j < 4; ++j) { const int c = 8 * lane + 512 * (j >> 1) + 4 * (j & 1); sh[j] = *(const f32x4*)(a.mod_nxt + moff + a.sh_off + c); sc[j] = *(const f32x4*)(a.mod_nxt + moff + a.sc_off + c); }
;             }
;         }
;         __builtin_amdgcn_sched_barrier(0);
;         if (a.copy_x) {
; #pragma unroll
;             for (int u = 0; u < 2; ++u)
; #pragma unroll
;                 for (int jb = 0; jb < 2; ++jb) { u32x4 w; w.x = cvt_pk_bf16(v[u][2 * jb][0], v[u][2 * jb][1]); w.y = cvt_pk_bf16(v[u][2 * jb][2], v[u][2 * jb][3]);
;                     w.z = cvt_pk_bf16(v[u][2 * jb + 1][0], v[u][2 * jb + 1][1]); w.w = cvt_pk_bf16(v[u][2 * jb + 1][2], v[u][2 * jb + 1][3]);
;                     *(u32x4*)((bf16_t*)xob + xoff + u * DM + 8 * lane + 512 * jb) = w; v[u][2 * jb] = bfx4_lo(w); v[u][2 * jb + 1] = bfx4_hi(w); }
;         }
;         if (use_y) {
; #pragma unroll
;             for (int u = 0; u < 2; ++u) {
;                 float s = 0.f;
; #pragma unroll
.LBB0_220:
	v_and_b32_e32 v145, 64, v221
	v_xor_b32_e32 v146, 16, v221
	v_add_u32_e32 v145, 64, v145
	s_cmp_lg_u32 s32, 0
	s_cbranch_scc0 .Lrt0_205
	s_nop 0
	s_waitcnt vmcnt(0)
	s_branch .Lrt1_205

; __device__ __forceinline__ f32x4 bfx4_lo(u32x4 w) { return (f32x4){bf_lo(w.x), bf_hi(w.x), bf_lo(w.y), bf_hi(w.y)}; }
; __device__ __forceinline__ void phase_rows(const Params& p, const RowArgs& a, int G, int wave, int lane) {
;     ...
;         if (bmaj) mp = (it < ppw) ? (gw / wpb) * (SEQ / 2) + (gw % wpb) + it * wpb : ML / 2 + gw + (it - ppw) * NGW;
;         else mp = ((a.ctx_only && !bmaj) ? ML / 2 : 0) + gw + it * NGW;
;         if (mp >= a.nrows / 2) break;
;         const int m0 = 2 * mp; const bool isl = m0 < ML; const int rb = isl ? (m0 >> 12) : 8;
;         const bool use_y = a.has_y && !(a.lat_no_y && isl);
;         const size_t xoff = isl ? (size_t)m0 * DM : (size_t)(m0 - ML) * DM;
;         const void* xrb = isl ? a.xlat : a.xctx; void* xob = isl ? a.olat : a.octx;
;         bf16_t* xn = XN + (size_t)m0 * DM;
;         const size_t moff = (size_t)rb * NMOD;
;         f32x4 v[2][4], y[2][4];
;         if (a.xin_f32) {
; #pragma unroll
;             for (int u = 0; u < 2; ++u)
; #pragma unroll
;                 for (int j = 0; j < 4; ++j) v[u][j] = *(const f32x4*)((const float*)xrb + xoff + u * DM + 8 * lane + 512 * (j >> 1) + 4 * (j & 1));
;         } else {
; #pragma unroll
;             for (int u = 0; u < 2; ++u)
; #pragma unroll
;                 for (int jb = 0; jb < 2; ++jb) { const u32x4 xw = *(const u32x4*)((const bf16_t*)xrb + xoff + u * DM + 8 * lane + 512 * jb); v[u][2 * jb] = bfx4_lo(xw); v[u][2 * jb + 1] = bfx4_hi(xw); }
;         }
;         if (use_y) {
;             if (isl || !a.ctx_split) {
; #pragma unroll
;                 for (int u = 0; u < 2; ++u)
; #pragma unroll
;                     for (int jb = 0; jb < 2; ++jb) { const u32x4 yw = *(const u32x4*)(xn + u * DM + 8 * lane + 512 * jb); y[u][2 * jb] = bfx4_lo(yw); y[u][2 * jb + 1] = bfx4_hi(yw); }
;             } else {
;                 const float* part = (const float*)p.out;
; #pragma unroll
;                 for (int u = 0; u < 2; ++u)
; #pragma unroll
;                     for (int j = 0; j < 4; ++j) { const float* pp = part + (size_t)(m0 + u - ML) * DM + 8 * lane + 512 * (j >> 1) + 4 * (j & 1); f32x4 s = *(const f32x4*)pp;
; #pragma unroll
;                         for (int k = 1; k < pg8::KSPLIT; ++k) s += *(const f32x4*)(pp + (size_t)k * MC * DM);
;                         y[u][j] = s; }
;             }
.LBB0_327:
	s_cmpk_gt_i32 s11, 0x43ff
	s_mov_b64 s[0:1], -1
	s_cbranch_scc1 .LBB0_321
	s_lshl_b32 s4, s11, 1
	s_cmpk_lt_i32 s11, 0x4000
	s_cselect_b64 s[0:1], -1, 0
	s_ashr_i32 s5, s4, 31
	s_add_i32 s30, s4, 0xffff8000
	s_cmpk_gt_i32 s11, 0x3fff
	s_cselect_b64 s[8:9], -1, 0
	s_and_b64 s[6:7], s[8:9], exec
	s_cselect_b32 s7, 0, s5
	s_cselect_b32 s6, s30, s4
	s_cselect_b32 s21, s99, s79
	s_cselect_b32 s24, s98, s78
	s_lshl_b64 s[22:23], s[6:7], 11
	s_add_u32 s22, s24, s22
	s_addc_u32 s23, s21, s23
	global_load_dwordx4 v[116:119], v170, s[22:23] nt
	global_load_dwordx4 v[112:115], v170, s[22:23] offset:1024 nt
	global_load_dwordx4 v[108:111], v170, s[22:23] offset:2048 nt
	global_load_dwordx4 v[104:107], v170, s[22:23] offset:3072 nt
	v_lshl_add_u64 v[248:249], s[22:23], 0, v[250:251]
	s_add_i32 s32, s11, s52
	s_cmpk_lt_i32 s32, 0x4000
	s_cselect_b32 s32, 1, 0
	v_readlane_b32 vcc_lo, v254, 17
	s_nop 0
	s_and_b32 s32, s32, vcc_lo
	s_and_b64 vcc, exec, s[0:1]
	s_cbranch_vccnz .LBB0_330
	s_lshl_b64 s[22:23], s[30:31], 12
	v_lshl_add_u64 v[88:89], v[176:177], 0, s[22:23]
	v_add_co_u32_e32 v96, vcc, 0x800000, v88
	global_load_dwordx4 v[84:87], v[88:89], off offset:16
	global_load_dwordx4 v[80:83], v[88:89], off
	s_mov_b64 s[24:25], 0x800000
	v_addc_co_u32_e32 v97, vcc, 0, v89, vcc
	v_lshl_add_u64 v[94:95], v[88:89], 0, s[24:25]
	global_load_dwordx4 v[90:93], v[96:97], off
	global_load_dwordx4 v[126:129], v[94:95], off offset:16
	s_mov_b64 s[26:27], 0x1000000
	v_add_co_u32_e32 v120, vcc, 0x1000000, v88
	s_mov_b64 s[28:29], 0x1800000
	s_nop 0
	v_addc_co_u32_e32 v121, vcc, 0, v89, vcc
	v_add_co_u32_e32 v122, vcc, 0x1800000, v88
	v_lshl_add_u64 v[100:101], v[88:89], 0, s[28:29]
	s_nop 0
	v_addc_co_u32_e32 v123, vcc, 0, v89, vcc
	v_add_co_u32_e32 v102, vcc, 0x2000000, v88
	s_mov_b64 s[34:35], 0x2000000
	s_nop 0
	v_addc_co_u32_e32 v103, vcc, 0, v89, vcc
	v_add_co_u32_e32 v124, vcc, 0x2800000, v88
	s_mov_b64 s[62:63], 0x2800000
	s_nop 0
	v_addc_co_u32_e32 v125, vcc, 0, v89, vcc
	s_mov_b64 s[64:65], 0x3000000
	v_lshl_add_u64 v[142:143], v[88:89], 0, s[64:65]
	s_mov_b64 s[68:69], 0x3800000
	v_lshl_add_u64 v[146:147], v[88:89], 0, s[68:69]
	s_mov_b64 s[70:71], 0x800800
	s_mov_b64 s[74:75], 0x1000800
	s_mov_b64 s[76:77], 0x1800800
	s_mov_b64 s[94:95], 0x2000800
	s_mov_b64 s[16:17], 0x2800800
	s_mov_b32 s38, s96
	s_mov_b64 s[96:97], 0x3000800
	s_mov_b64 s[36:37], 0x3800800
	s_add_i32 s30, s4, 0xffff8001
	s_lshl_b64 s[22:23], s[30:31], 12
	s_mov_b32 s21, 0x1000000
	s_waitcnt vmcnt(1)
	v_pk_add_f32 v[98:99], v[82:83], v[92:93]
	v_lshl_add_u64 v[92:93], v[88:89], 0, s[26:27]
	v_pk_add_f32 v[90:91], v[80:81], v[90:91]
	global_load_dwordx4 v[80:83], v[120:121], off
	s_nop 0
	global_load_dwordx4 v[92:95], v[92:93], off offset:16
	s_waitcnt vmcnt(2)
	v_pk_add_f32 v[86:87], v[86:87], v[128:129]
	v_pk_add_f32 v[84:85], v[84:85], v[126:127]
	s_waitcnt vmcnt(1)
	v_pk_add_f32 v[98:99], v[98:99], v[82:83]
	v_pk_add_f32 v[90:91], v[90:91], v[80:81]
	global_load_dwordx4 v[80:83], v[122:123], off
	global_load_dwordx4 v[130:133], v[100:101], off offset:16
	v_lshl_add_u64 v[100:101], v[88:89], 0, s[34:35]
	s_waitcnt vmcnt(2)
	v_pk_add_f32 v[86:87], v[86:87], v[94:95]
	v_pk_add_f32 v[84:85], v[84:85], v[92:93]
	s_waitcnt vmcnt(1)
	v_pk_add_f32 v[98:99], v[98:99], v[82:83]
	v_pk_add_f32 v[90:91], v[90:91], v[80:81]
	global_load_dwordx4 v[80:83], v[102:103], off
	global_load_dwordx4 v[134:137], v[100:101], off offset:16
	v_lshl_add_u64 v[100:101], v[88:89], 0, s[62:63]
	s_waitcnt vmcnt(2)
	v_pk_add_f32 v[86:87], v[86:87], v[132:133]
	v_pk_add_f32 v[84:85], v[84:85], v[130:131]
	s_waitcnt vmcnt(1)
	v_pk_add_f32 v[98:99], v[98:99], v[82:83]
	v_pk_add_f32 v[90:91], v[90:91], v[80:81]
	global_load_dwordx4 v[80:83], v[124:125], off
	global_load_dwordx4 v[138:141], v[100:101], off offset:16
	v_add_co_u32_e32 v100, vcc, 0x3000000, v88
	s_waitcnt vmcnt(2)
	v_pk_add_f32 v[86:87], v[86:87], v[136:137]
	v_addc_co_u32_e32 v101, vcc, 0, v89, vcc
	v_pk_add_f32 v[84:85], v[84:85], v[134:135]
	s_waitcnt vmcnt(1)
	v_pk_add_f32 v[98:99], v[98:99], v[82:83]
	v_pk_add_f32 v[90:91], v[90:91], v[80:81]
	global_load_dwordx4 v[80:83], v[100:101], off
	s_nop 0
	global_load_dwordx4 v[142:145], v[142:143], off offset:16
	s_waitcnt vmcnt(2)
	v_pk_add_f32 v[84:85], v[84:85], v[138:139]
	v_pk_add_f32 v[86:87], v[86:87], v[140:141]
	s_waitcnt vmcnt(1)
	v_pk_add_f32 v[150:151], v[90:91], v[80:81]
	v_add_co_u32_e32 v90, vcc, 0x3800000, v88
	v_pk_add_f32 v[98:99], v[98:99], v[82:83]
	s_nop 0
	v_addc_co_u32_e32 v91, vcc, 0, v89, vcc
	global_load_dwordx4 v[80:83], v[90:91], off
	s_nop 0
	global_load_dwordx4 v[146:149], v[146:147], off offset:16
	s_nop 0
	global_load_dwordx4 v[92:95], v[88:89], off offset:2064
	global_load_dwordx4 v[126:129], v[88:89], off offset:2048
	s_waitcnt vmcnt(4)
	v_pk_add_f32 v[84:85], v[84:85], v[142:143]
	v_pk_add_f32 v[86:87], v[86:87], v[144:145]
	s_waitcnt vmcnt(3)
	v_pk_add_f32 v[82:83], v[98:99], v[82:83]
	v_lshl_add_u64 v[98:99], v[88:89], 0, s[70:71]
	global_load_dwordx4 v[130:133], v[96:97], off offset:2048
	s_nop 0
	global_load_dwordx4 v[96:99], v[98:99], off offset:16
	s_waitcnt vmcnt(4)
	v_pk_add_f32 v[86:87], v[86:87], v[148:149]
	v_pk_add_f32 v[84:85], v[84:85], v[146:147]
	v_pk_add_f32 v[80:81], v[150:151], v[80:81]
	s_waitcnt vmcnt(1)
	v_pk_add_f32 v[136:137], v[126:127], v[130:131]
	v_lshl_add_u64 v[130:131], v[88:89], 0, s[74:75]
	v_pk_add_f32 v[134:135], v[128:129], v[132:133]
	global_load_dwordx4 v[126:129], v[120:121], off offset:2048
	s_nop 0
	global_load_dwordx4 v[130:133], v[130:131], off offset:16
	s_waitcnt vmcnt(2)
; __device__ __forceinline__ void phase_rows(const Params& p, const RowArgs& a, int G, int wave, int lane) {
;     ...
;                 const float* part = (const float*)p.out;
; #pragma unroll
;                 for (int u = 0; u < 2; ++u)
; #pragma unroll
;                     for (int j = 0; j < 4; ++j) { const float* pp = part + (size_t)(m0 + u - ML) * DM + 8 * lane + 512 * (j >> 1) + 4 * (j & 1); f32x4 s = *(const f32x4*)pp;
; #pragma unroll
;                         for (int k = 1; k < pg8::KSPLIT; ++k) s += *(const f32x4*)(pp + (size_t)k * MC * DM);
;                         y[u][j] = s; }
;             }
	v_pk_add_f32 v[92:93], v[92:93], v[96:97]
	v_pk_add_f32 v[94:95], v[94:95], v[98:99]
	s_waitcnt vmcnt(1)
	v_pk_add_f32 v[136:137], v[136:137], v[126:127]
	v_lshl_add_u64 v[126:127], v[88:89], 0, s[76:77]
	v_pk_add_f32 v[134:135], v[134:135], v[128:129]
	global_load_dwordx4 v[120:123], v[122:123], off offset:2048
	s_nop 0
	global_load_dwordx4 v[126:129], v[126:127], off offset:16
	s_waitcnt vmcnt(2)
	v_pk_add_f32 v[92:93], v[92:93], v[130:131]
	v_pk_add_f32 v[94:95], v[94:95], v[132:133]
	s_waitcnt vmcnt(1)
	v_pk_add_f32 v[138:139], v[134:135], v[122:123]
	v_lshl_add_u64 v[134:135], v[88:89], 0, s[94:95]
	v_pk_add_f32 v[140:141], v[136:137], v[120:121]
	global_load_dwordx4 v[120:123], v[102:103], off offset:2048
	s_nop 0
	global_load_dwordx4 v[134:137], v[134:135], off offset:16
	s_waitcnt vmcnt(2)
	v_pk_add_f32 v[92:93], v[92:93], v[126:127]
	v_pk_add_f32 v[94:95], v[94:95], v[128:129]
	s_waitcnt vmcnt(1)
	v_pk_add_f32 v[102:103], v[138:139], v[122:123]
	v_lshl_add_u64 v[138:139], v[88:89], 0, s[16:17]
	v_pk_add_f32 v[142:143], v[140:141], v[120:121]
	global_load_dwordx4 v[120:123], v[124:125], off offset:2048
	s_nop 0
	global_load_dwordx4 v[138:141], v[138:139], off offset:16
	s_waitcnt vmcnt(2)
	v_pk_add_f32 v[92:93], v[92:93], v[134:135]
	v_pk_add_f32 v[94:95], v[94:95], v[136:137]
	s_waitcnt vmcnt(1)
	v_pk_add_f32 v[142:143], v[142:143], v[120:121]
	v_lshl_add_u64 v[120:121], v[88:89], 0, s[96:97]
	v_pk_add_f32 v[124:125], v[102:103], v[122:123]
	global_load_dwordx4 v[100:103], v[100:101], off offset:2048
	s_nop 0
	global_load_dwordx4 v[120:123], v[120:121], off offset:16
	s_waitcnt vmcnt(2)
	v_pk_add_f32 v[92:93], v[92:93], v[138:139]
	v_pk_add_f32 v[94:95], v[94:95], v[140:141]
	s_waitcnt vmcnt(1)
	v_pk_add_f32 v[142:143], v[142:143], v[100:101]
	v_lshl_add_u64 v[100:101], v[88:89], 0, s[36:37]
	v_pk_add_f32 v[124:125], v[124:125], v[102:103]
	global_load_dwordx4 v[88:91], v[90:91], off offset:2048
	s_nop 0
	global_load_dwordx4 v[100:103], v[100:101], off offset:16
	s_waitcnt vmcnt(2)
	v_pk_add_f32 v[92:93], v[92:93], v[120:121]
	v_lshl_add_u64 v[120:121], v[176:177], 0, s[22:23]
	v_pk_add_f32 v[94:95], v[94:95], v[122:123]
	v_add_co_u32_e32 v122, vcc, s55, v120
	v_lshl_add_u64 v[128:129], v[120:121], 0, s[24:25]
	s_nop 0
	v_addc_co_u32_e32 v123, vcc, 0, v121, vcc
	v_add_co_u32_e32 v132, vcc, s21, v120
	s_mov_b32 s21, 0x1800000
	s_nop 0
	v_addc_co_u32_e32 v133, vcc, 0, v121, vcc
	v_lshl_add_u64 v[140:141], v[120:121], 0, s[28:29]
	s_waitcnt vmcnt(1)
	v_pk_add_f32 v[90:91], v[124:125], v[90:91]
	s_waitcnt vmcnt(0)
	v_pk_add_f32 v[94:95], v[94:95], v[102:103]
	v_pk_add_f32 v[92:93], v[92:93], v[100:101]
	global_load_dwordx4 v[100:103], v[120:121], off offset:16
	global_load_dwordx4 v[96:99], v[120:121], off
	global_load_dwordx4 v[124:127], v[122:123], off
	s_nop 0
	global_load_dwordx4 v[128:131], v[128:129], off offset:16
	v_pk_add_f32 v[88:89], v[142:143], v[88:89]
	v_lshl_add_u64 v[142:143], v[120:121], 0, s[34:35]
	s_waitcnt vmcnt(1)
	v_pk_add_f32 v[136:137], v[96:97], v[124:125]
	v_lshl_add_u64 v[124:125], v[120:121], 0, s[26:27]
	v_pk_add_f32 v[134:135], v[98:99], v[126:127]
	global_load_dwordx4 v[96:99], v[132:133], off
	s_nop 0
	global_load_dwordx4 v[124:127], v[124:125], off offset:16
	s_waitcnt vmcnt(2)
	v_pk_add_f32 v[102:103], v[102:103], v[130:131]
	v_pk_add_f32 v[100:101], v[100:101], v[128:129]
	v_lshl_add_u64 v[128:129], v[120:121], 0, s[70:71]
	s_waitcnt vmcnt(1)
	v_pk_add_f32 v[138:139], v[136:137], v[96:97]
	v_add_co_u32_e32 v136, vcc, s21, v120
	v_pk_add_f32 v[134:135], v[134:135], v[98:99]
	s_nop 0
	v_addc_co_u32_e32 v137, vcc, 0, v121, vcc
	global_load_dwordx4 v[96:99], v[136:137], off
	global_load_dwordx4 v[178:181], v[140:141], off offset:16
	s_brev_b32 s21, 64
	v_add_co_u32_e32 v140, vcc, s21, v120
	s_mov_b32 s21, 0x2800000
	s_nop 0
	v_addc_co_u32_e32 v141, vcc, 0, v121, vcc
	v_add_co_u32_e32 v144, vcc, s21, v120
	s_mov_b32 s21, 0x3000000
	s_nop 0
	v_addc_co_u32_e32 v145, vcc, 0, v121, vcc
	v_add_co_u32_e32 v148, vcc, s21, v120
	s_mov_b32 s21, 0x3800000
	s_nop 0
	v_addc_co_u32_e32 v149, vcc, 0, v121, vcc
	v_add_co_u32_e32 v152, vcc, s21, v120
	s_waitcnt vmcnt(2)
	v_pk_add_f32 v[102:103], v[102:103], v[126:127]
	v_addc_co_u32_e32 v153, vcc, 0, v121, vcc
	v_pk_add_f32 v[100:101], v[100:101], v[124:125]
	s_waitcnt vmcnt(1)
	v_pk_add_f32 v[134:135], v[134:135], v[98:99]
	v_pk_add_f32 v[138:139], v[138:139], v[96:97]
	global_load_dwordx4 v[96:99], v[140:141], off
	global_load_dwordx4 v[182:185], v[142:143], off offset:16
	v_lshl_add_u64 v[142:143], v[120:121], 0, s[62:63]
	s_waitcnt vmcnt(2)
; __device__ __forceinline__ void phase_rows(const Params& p, const RowArgs& a, int G, int wave, int lane) {
;     ...
;                 const float* part = (const float*)p.out;
; #pragma unroll
;                 for (int u = 0; u < 2; ++u)
; #pragma unroll
;                     for (int j = 0; j < 4; ++j) { const float* pp = part + (size_t)(m0 + u - ML) * DM + 8 * lane + 512 * (j >> 1) + 4 * (j & 1); f32x4 s = *(const f32x4*)pp;
; #pragma unroll
;                         for (int k = 1; k < pg8::KSPLIT; ++k) s += *(const f32x4*)(pp + (size_t)k * MC * DM);
;                         y[u][j] = s; }
;             }
	v_pk_add_f32 v[102:103], v[102:103], v[180:181]
	v_pk_add_f32 v[100:101], v[100:101], v[178:179]
	s_waitcnt vmcnt(1)
	v_pk_add_f32 v[134:135], v[134:135], v[98:99]
	v_pk_add_f32 v[138:139], v[138:139], v[96:97]
	global_load_dwordx4 v[96:99], v[144:145], off
	global_load_dwordx4 v[186:189], v[142:143], off offset:16
	v_lshl_add_u64 v[142:143], v[120:121], 0, s[64:65]
	s_waitcnt vmcnt(2)
	v_pk_add_f32 v[102:103], v[102:103], v[184:185]
	v_pk_add_f32 v[100:101], v[100:101], v[182:183]
	s_waitcnt vmcnt(1)
	v_pk_add_f32 v[134:135], v[134:135], v[98:99]
	v_pk_add_f32 v[138:139], v[138:139], v[96:97]
	global_load_dwordx4 v[96:99], v[148:149], off
	global_load_dwordx4 v[190:193], v[142:143], off offset:16
	v_lshl_add_u64 v[142:143], v[120:121], 0, s[68:69]
	s_waitcnt vmcnt(2)
	v_pk_add_f32 v[102:103], v[102:103], v[188:189]
	v_pk_add_f32 v[100:101], v[100:101], v[186:187]
	s_waitcnt vmcnt(1)
	v_pk_add_f32 v[134:135], v[134:135], v[98:99]
	v_pk_add_f32 v[138:139], v[138:139], v[96:97]
	global_load_dwordx4 v[96:99], v[152:153], off
	global_load_dwordx4 v[194:197], v[142:143], off offset:16
	global_load_dwordx4 v[124:127], v[120:121], off offset:2064
	global_load_dwordx4 v[178:181], v[120:121], off offset:2048
	global_load_dwordx4 v[182:185], v[122:123], off offset:2048
	s_nop 0
	global_load_dwordx4 v[128:131], v[128:129], off offset:16
	s_waitcnt vmcnt(6)
	v_pk_add_f32 v[102:103], v[102:103], v[192:193]
	v_pk_add_f32 v[100:101], v[100:101], v[190:191]
	s_waitcnt vmcnt(5)
	v_pk_add_f32 v[98:99], v[134:135], v[98:99]
	v_lshl_add_u64 v[134:135], v[120:121], 0, s[74:75]
	v_pk_add_f32 v[96:97], v[138:139], v[96:97]
	s_waitcnt vmcnt(1)
	v_pk_add_f32 v[122:123], v[180:181], v[184:185]
	v_pk_add_f32 v[138:139], v[178:179], v[182:183]
	global_load_dwordx4 v[178:181], v[132:133], off offset:2048
	s_nop 0
	global_load_dwordx4 v[132:135], v[134:135], off offset:16
	s_waitcnt vmcnt(2)
	v_pk_add_f32 v[126:127], v[126:127], v[130:131]
	v_pk_add_f32 v[124:125], v[124:125], v[128:129]
	v_pk_add_f32 v[102:103], v[102:103], v[196:197]
	v_pk_add_f32 v[100:101], v[100:101], v[194:195]
	s_waitcnt vmcnt(1)
	v_pk_add_f32 v[142:143], v[138:139], v[178:179]
	v_lshl_add_u64 v[138:139], v[120:121], 0, s[76:77]
	v_pk_add_f32 v[122:123], v[122:123], v[180:181]
	global_load_dwordx4 v[178:181], v[136:137], off offset:2048
	s_nop 0
	global_load_dwordx4 v[136:139], v[138:139], off offset:16
	s_waitcnt vmcnt(2)
	v_pk_add_f32 v[126:127], v[126:127], v[134:135]
	v_pk_add_f32 v[124:125], v[124:125], v[132:133]
	s_waitcnt vmcnt(1)
	v_pk_add_f32 v[146:147], v[142:143], v[178:179]
	v_lshl_add_u64 v[142:143], v[120:121], 0, s[94:95]
	v_pk_add_f32 v[122:123], v[122:123], v[180:181]
	global_load_dwordx4 v[178:181], v[140:141], off offset:2048
	s_nop 0
	global_load_dwordx4 v[140:143], v[142:143], off offset:16
	s_waitcnt vmcnt(2)
	v_pk_add_f32 v[126:127], v[126:127], v[138:139]
	v_pk_add_f32 v[124:125], v[124:125], v[136:137]
	v_readlane_b32 s94, v255, 27
	v_readlane_b32 s95, v255, 28
	s_waitcnt vmcnt(1)
	v_pk_add_f32 v[150:151], v[146:147], v[178:179]
	v_lshl_add_u64 v[146:147], v[120:121], 0, s[16:17]
	v_pk_add_f32 v[122:123], v[122:123], v[180:181]
	global_load_dwordx4 v[178:181], v[144:145], off offset:2048
	s_nop 0
	global_load_dwordx4 v[144:147], v[146:147], off offset:16
	s_waitcnt vmcnt(2)
	v_pk_add_f32 v[126:127], v[126:127], v[142:143]
	v_pk_add_f32 v[124:125], v[124:125], v[140:141]
	s_waitcnt vmcnt(1)
	v_pk_add_f32 v[154:155], v[150:151], v[178:179]
	v_lshl_add_u64 v[150:151], v[120:121], 0, s[96:97]
	v_pk_add_f32 v[122:123], v[122:123], v[180:181]
	global_load_dwordx4 v[180:183], v[148:149], off offset:2048
	s_nop 0
	global_load_dwordx4 v[148:151], v[150:151], off offset:16
	s_waitcnt vmcnt(2)
	v_pk_add_f32 v[126:127], v[126:127], v[146:147]
	v_pk_add_f32 v[124:125], v[124:125], v[144:145]
	s_mov_b32 s96, s38
	s_waitcnt vmcnt(1)
	v_pk_add_f32 v[180:181], v[154:155], v[180:181]
	v_lshl_add_u64 v[154:155], v[120:121], 0, s[36:37]
	v_pk_add_f32 v[178:179], v[122:123], v[182:183]
	global_load_dwordx4 v[120:123], v[152:153], off offset:2048
	s_nop 0
	global_load_dwordx4 v[152:155], v[154:155], off offset:16
	s_waitcnt vmcnt(2)
	v_pk_add_f32 v[126:127], v[126:127], v[150:151]
	v_pk_add_f32 v[124:125], v[124:125], v[148:149]
	s_waitcnt vmcnt(1)
	v_pk_add_f32 v[122:123], v[178:179], v[122:123]
	v_pk_add_f32 v[120:121], v[180:181], v[120:121]
	s_waitcnt vmcnt(0)
	v_pk_add_f32 v[126:127], v[126:127], v[154:155]
	v_pk_add_f32 v[124:125], v[124:125], v[152:153]

; __device__ __forceinline__ void mod_item(const Params& p, LAS unsigned char* lds, int item, int tid, int wave, int lane) {
;     ...
;     const float* wp = p.in[I_WMOD] + (size_t)l * DM * NMOD + (size_t)(wave * 128) * NMOD + j0 + 4 * lane;
; #pragma unroll 1
;     for (int k8 = 0; k8 < 128; k8 += 8) {
;         f32x4 wv[8];
; #pragma unroll
;         for (int u = 0; u < 8; ++u) wv[u] = *(const f32x4*)(wp + (size_t)(k8 + u) * NMOD);
; #pragma unroll
;         for (int u = 0; u < 8; ++u)
; #pragma unroll
;             for (int r = 0; r < 9; ++r) { const float s = sv[r * 1024 + wave * 128 + k8 + u]; acc[r] += wv[u] * s; }
;     }
.LBB0_374:
	global_load_dwordx4 v[170:173], v[80:81], off nt
	v_add_co_u32_e32 v154, vcc, 0x6000, v80
	s_nop 1
	v_addc_co_u32_e32 v155, vcc, 0, v81, vcc
	global_load_dwordx4 v[174:177], v[154:155], off nt
	v_add_co_u32_e32 v154, vcc, 0x6000, v154
	s_nop 1
	v_addc_co_u32_e32 v155, vcc, 0, v155, vcc
	global_load_dwordx4 v[178:181], v[154:155], off nt
	v_add_co_u32_e32 v154, vcc, 0x6000, v154
	s_nop 1
	v_addc_co_u32_e32 v155, vcc, 0, v155, vcc
	global_load_dwordx4 v[182:185], v[154:155], off nt
	v_add_co_u32_e32 v154, vcc, 0x6000, v154
	s_nop 1
	v_addc_co_u32_e32 v155, vcc, 0, v155, vcc
	global_load_dwordx4 v[186:189], v[154:155], off nt
	v_add_co_u32_e32 v154, vcc, 0x6000, v154
	s_nop 1
	v_addc_co_u32_e32 v155, vcc, 0, v155, vcc
	global_load_dwordx4 v[190:193], v[154:155], off nt
	v_add_co_u32_e32 v154, vcc, 0x6000, v154
	s_nop 1
	v_addc_co_u32_e32 v155, vcc, 0, v155, vcc
	global_load_dwordx4 v[194:197], v[154:155], off nt
	v_add_co_u32_e32 v154, vcc, 0x6000, v154
	s_nop 1
	v_addc_co_u32_e32 v155, vcc, 0, v155, vcc
	global_load_dwordx4 v[198:201], v[154:155], off nt
	v_mov_b32_e32 v122, s12
	ds_read_b128 v[8:11], v122
	ds_read_b128 v[16:19], v122 offset:16
	ds_read_b128 v[40:43], v122 offset:4096
	ds_read_b128 v[44:47], v122 offset:8192
	ds_read_b128 v[20:23], v122 offset:4112
	ds_read_b128 v[24:27], v122 offset:8208
	s_movk_i32 s13, 0x6000
	s_add_i32 s11, s11, 8
	s_add_i32 s12, s12, 32
	s_mov_b64 s[14:15], 0x30000
	s_cmpk_gt_u32 s11, 0x77
	s_waitcnt vmcnt(7) lgkmcnt(2)
	v_mov_b32_e32 v118, v170
	v_mov_b32_e32 v119, v171
	v_mov_b32_e32 v120, v172
	v_mov_b32_e32 v121, v173
	v_pk_fma_f32 v[90:91], v[120:121], v[44:45], v[30:31] op_sel_hi:[1,0,1]
	v_pk_fma_f32 v[92:93], v[118:119], v[44:45], v[28:29] op_sel_hi:[1,0,1]
	ds_read_b128 v[48:51], v122 offset:12288
	ds_read_b128 v[28:31], v122 offset:12304
	v_pk_fma_f32 v[86:87], v[120:121], v[40:41], v[6:7] op_sel_hi:[1,0,1]
	v_pk_fma_f32 v[88:89], v[118:119], v[40:41], v[4:5] op_sel_hi:[1,0,1]
	v_pk_fma_f32 v[82:83], v[120:121], v[8:9], v[2:3] op_sel_hi:[1,0,1]
	s_waitcnt lgkmcnt(1)
	v_pk_fma_f32 v[94:95], v[120:121], v[48:49], v[34:35] op_sel_hi:[1,0,1]
	v_pk_fma_f32 v[96:97], v[118:119], v[48:49], v[32:33] op_sel_hi:[1,0,1]
	ds_read_b128 v[52:55], v122 offset:16384
	ds_read_b128 v[32:35], v122 offset:16400
	v_pk_fma_f32 v[84:85], v[118:119], v[8:9], v[0:1] op_sel_hi:[1,0,1]
	s_waitcnt lgkmcnt(1)
	v_pk_fma_f32 v[98:99], v[120:121], v[52:53], v[38:39] op_sel_hi:[1,0,1]
	v_pk_fma_f32 v[100:101], v[118:119], v[52:53], v[36:37] op_sel_hi:[1,0,1]
	ds_read_b128 v[56:59], v122 offset:20480
	ds_read_b128 v[36:39], v122 offset:20496
	s_waitcnt lgkmcnt(1)
	v_pk_fma_f32 v[102:103], v[120:121], v[56:57], v[62:63] op_sel_hi:[1,0,1]
	v_pk_fma_f32 v[104:105], v[118:119], v[56:57], v[60:61] op_sel_hi:[1,0,1]
	ds_read_b128 v[60:63], v122 offset:24576
	ds_read_b128 v[12:15], v122 offset:24592
	s_waitcnt lgkmcnt(1)
	v_pk_fma_f32 v[106:107], v[120:121], v[60:61], v[66:67] op_sel_hi:[1,0,1]
	v_pk_fma_f32 v[108:109], v[118:119], v[60:61], v[64:65] op_sel_hi:[1,0,1]
	ds_read_b128 v[64:67], v122 offset:28672
	ds_read_b128 v[4:7], v122 offset:28688
	s_waitcnt lgkmcnt(1)
	v_pk_fma_f32 v[110:111], v[120:121], v[64:65], v[70:71] op_sel_hi:[1,0,1]
	v_pk_fma_f32 v[112:113], v[118:119], v[64:65], v[68:69] op_sel_hi:[1,0,1]
	ds_read_b128 v[68:71], v122 offset:32768
	ds_read_b128 v[0:3], v122 offset:32784
	s_waitcnt lgkmcnt(1)
	v_pk_fma_f32 v[72:73], v[118:119], v[68:69], v[72:73] op_sel_hi:[1,0,1]
	v_add_co_u32_e32 v118, vcc, s13, v80
	s_mov_b32 s13, 0xc000
	s_nop 0
	v_addc_co_u32_e32 v119, vcc, 0, v81, vcc
	v_add_co_u32_e32 v122, vcc, s13, v80
	v_pk_fma_f32 v[74:75], v[120:121], v[68:69], v[74:75] op_sel_hi:[1,0,1]
	s_nop 0
	v_addc_co_u32_e32 v123, vcc, 0, v81, vcc
	s_nop 0
	s_nop 0
	s_nop 0
	s_mov_b32 s13, 0x12000
	s_waitcnt vmcnt(6)
	v_mov_b32_e32 v118, v174
	v_mov_b32_e32 v119, v175
	v_mov_b32_e32 v120, v176
	v_mov_b32_e32 v121, v177
	v_pk_fma_f32 v[82:83], v[120:121], v[8:9], v[82:83] op_sel:[0,1,0]
	v_pk_fma_f32 v[8:9], v[118:119], v[8:9], v[84:85] op_sel:[0,1,0]
	v_pk_fma_f32 v[74:75], v[120:121], v[68:69], v[74:75] op_sel:[0,1,0]
	v_pk_fma_f32 v[68:69], v[118:119], v[68:69], v[72:73] op_sel:[0,1,0]
	s_waitcnt vmcnt(5)
	v_mov_b32_e32 v122, v178
	v_mov_b32_e32 v123, v179
	v_mov_b32_e32 v124, v180
	v_mov_b32_e32 v125, v181
	v_pk_fma_f32 v[72:73], v[124:125], v[10:11], v[82:83] op_sel_hi:[1,0,1]
	v_pk_fma_f32 v[82:83], v[122:123], v[10:11], v[8:9] op_sel_hi:[1,0,1]
	v_add_co_u32_e32 v8, vcc, s13, v80
	v_pk_fma_f32 v[84:85], v[120:121], v[40:41], v[86:87] op_sel:[0,1,0]
	v_pk_fma_f32 v[40:41], v[118:119], v[40:41], v[88:89] op_sel:[0,1,0]
	v_addc_co_u32_e32 v9, vcc, 0, v81, vcc
	s_mov_b32 s13, 0x18000
	v_pk_fma_f32 v[86:87], v[120:121], v[44:45], v[90:91] op_sel:[0,1,0]
	v_pk_fma_f32 v[90:91], v[120:121], v[52:53], v[98:99] op_sel:[0,1,0]
	v_pk_fma_f32 v[98:99], v[122:123], v[42:43], v[40:41] op_sel_hi:[1,0,1]
	v_add_co_u32_e32 v40, vcc, s13, v80
	v_pk_fma_f32 v[44:45], v[118:119], v[44:45], v[92:93] op_sel:[0,1,0]
	v_pk_fma_f32 v[88:89], v[120:121], v[48:49], v[94:95] op_sel:[0,1,0]
	v_pk_fma_f32 v[48:49], v[118:119], v[48:49], v[96:97] op_sel:[0,1,0]
	v_addc_co_u32_e32 v41, vcc, 0, v81, vcc
	v_pk_fma_f32 v[84:85], v[124:125], v[42:43], v[84:85] op_sel_hi:[1,0,1]
	v_pk_fma_f32 v[86:87], v[124:125], v[46:47], v[86:87] op_sel_hi:[1,0,1]
	v_pk_fma_f32 v[44:45], v[122:123], v[46:47], v[44:45] op_sel_hi:[1,0,1]
	v_pk_fma_f32 v[88:89], v[124:125], v[50:51], v[88:89] op_sel_hi:[1,0,1]
	v_pk_fma_f32 v[48:49], v[122:123], v[50:51], v[48:49] op_sel_hi:[1,0,1]
	v_mov_b32_e32 v46, v11
	v_mov_b32_e32 v50, v43
	s_nop 0
	s_nop 0
	s_nop 0
; __device__ __forceinline__ void mod_item(const Params& p, LAS unsigned char* lds, int item, int tid, int wave, int lane) {
;     ...
;         for (int u = 0; u < 8; ++u)
; #pragma unroll
;             for (int r = 0; r < 9; ++r) { const float s = sv[r * 1024 + wave * 128 + k8 + u]; acc[r] += wv[u] * s; }
	v_pk_fma_f32 v[52:53], v[118:119], v[52:53], v[100:101] op_sel:[0,1,0]
	v_pk_fma_f32 v[92:93], v[120:121], v[56:57], v[102:103] op_sel:[0,1,0]
	v_pk_fma_f32 v[56:57], v[118:119], v[56:57], v[104:105] op_sel:[0,1,0]
	v_pk_fma_f32 v[94:95], v[120:121], v[60:61], v[106:107] op_sel:[0,1,0]
	v_pk_fma_f32 v[60:61], v[118:119], v[60:61], v[108:109] op_sel:[0,1,0]
	v_pk_fma_f32 v[96:97], v[120:121], v[64:65], v[110:111] op_sel:[0,1,0]
	v_pk_fma_f32 v[64:65], v[118:119], v[64:65], v[112:113] op_sel:[0,1,0]
	v_pk_fma_f32 v[90:91], v[124:125], v[54:55], v[90:91] op_sel_hi:[1,0,1]
	v_pk_fma_f32 v[52:53], v[122:123], v[54:55], v[52:53] op_sel_hi:[1,0,1]
	v_pk_fma_f32 v[92:93], v[124:125], v[58:59], v[92:93] op_sel_hi:[1,0,1]
	v_pk_fma_f32 v[56:57], v[122:123], v[58:59], v[56:57] op_sel_hi:[1,0,1]
	v_pk_fma_f32 v[94:95], v[124:125], v[62:63], v[94:95] op_sel_hi:[1,0,1]
	v_pk_fma_f32 v[60:61], v[122:123], v[62:63], v[60:61] op_sel_hi:[1,0,1]
	v_pk_fma_f32 v[96:97], v[124:125], v[66:67], v[96:97] op_sel_hi:[1,0,1]
	v_pk_fma_f32 v[64:65], v[122:123], v[66:67], v[64:65] op_sel_hi:[1,0,1]
	v_pk_fma_f32 v[74:75], v[124:125], v[70:71], v[74:75] op_sel_hi:[1,0,1]
	v_pk_fma_f32 v[68:69], v[122:123], v[70:71], v[68:69] op_sel_hi:[1,0,1]
	v_mov_b32_e32 v54, v47
	v_mov_b32_e32 v58, v51
	v_mov_b32_e32 v62, v55
	v_mov_b32_e32 v66, v59
	v_mov_b32_e32 v70, v63
	v_mov_b32_e32 v100, v67
	v_mov_b32_e32 v102, v71
	s_mov_b32 s13, 0x1e000
	s_waitcnt vmcnt(4)
	v_mov_b32_e32 v8, v182
	v_mov_b32_e32 v9, v183
	v_mov_b32_e32 v10, v184
	v_mov_b32_e32 v11, v185
	v_pk_fma_f32 v[72:73], v[10:11], v[46:47], v[72:73] op_sel_hi:[1,0,1]
	v_pk_fma_f32 v[46:47], v[8:9], v[46:47], v[82:83] op_sel_hi:[1,0,1]
	v_pk_fma_f32 v[82:83], v[10:11], v[50:51], v[84:85] op_sel_hi:[1,0,1]
	v_pk_fma_f32 v[50:51], v[8:9], v[50:51], v[98:99] op_sel_hi:[1,0,1]
	v_pk_fma_f32 v[84:85], v[10:11], v[54:55], v[86:87] op_sel_hi:[1,0,1]
	v_pk_fma_f32 v[44:45], v[8:9], v[54:55], v[44:45] op_sel_hi:[1,0,1]
	v_pk_fma_f32 v[48:49], v[8:9], v[58:59], v[48:49] op_sel_hi:[1,0,1]
	v_pk_fma_f32 v[52:53], v[8:9], v[62:63], v[52:53] op_sel_hi:[1,0,1]
	v_pk_fma_f32 v[56:57], v[8:9], v[66:67], v[56:57] op_sel_hi:[1,0,1]
	v_pk_fma_f32 v[60:61], v[8:9], v[70:71], v[60:61] op_sel_hi:[1,0,1]
	v_pk_fma_f32 v[64:65], v[8:9], v[100:101], v[64:65] op_sel_hi:[1,0,1]
	v_pk_fma_f32 v[8:9], v[8:9], v[102:103], v[68:69] op_sel_hi:[1,0,1]
	v_pk_fma_f32 v[54:55], v[10:11], v[58:59], v[88:89] op_sel_hi:[1,0,1]
	v_pk_fma_f32 v[58:59], v[10:11], v[62:63], v[90:91] op_sel_hi:[1,0,1]
	v_pk_fma_f32 v[62:63], v[10:11], v[66:67], v[92:93] op_sel_hi:[1,0,1]
	v_pk_fma_f32 v[66:67], v[10:11], v[70:71], v[94:95] op_sel_hi:[1,0,1]
	v_pk_fma_f32 v[70:71], v[10:11], v[100:101], v[96:97] op_sel_hi:[1,0,1]
	v_pk_fma_f32 v[10:11], v[10:11], v[102:103], v[74:75] op_sel_hi:[1,0,1]
	s_waitcnt vmcnt(3)
	v_mov_b32_e32 v40, v186
	v_mov_b32_e32 v41, v187
	v_mov_b32_e32 v42, v188
	v_mov_b32_e32 v43, v189
	v_pk_fma_f32 v[74:75], v[42:43], v[24:25], v[84:85] op_sel_hi:[1,0,1]
	s_waitcnt lgkmcnt(0)
	v_pk_fma_f32 v[84:85], v[40:41], v[0:1], v[8:9] op_sel_hi:[1,0,1]
	v_add_co_u32_e32 v8, vcc, s13, v80
	s_mov_b32 s13, 0x24000
	s_nop 0
	v_addc_co_u32_e32 v9, vcc, 0, v81, vcc
	v_pk_fma_f32 v[68:69], v[42:43], v[16:17], v[72:73] op_sel_hi:[1,0,1]
	v_pk_fma_f32 v[72:73], v[42:43], v[20:21], v[82:83] op_sel_hi:[1,0,1]
	v_pk_fma_f32 v[82:83], v[42:43], v[0:1], v[10:11] op_sel_hi:[1,0,1]
	v_add_co_u32_e32 v10, vcc, s13, v80
	v_pk_fma_f32 v[46:47], v[40:41], v[16:17], v[46:47] op_sel_hi:[1,0,1]
	s_nop 0
	v_addc_co_u32_e32 v11, vcc, 0, v81, vcc
	v_pk_fma_f32 v[50:51], v[40:41], v[20:21], v[50:51] op_sel_hi:[1,0,1]
	v_pk_fma_f32 v[44:45], v[40:41], v[24:25], v[44:45] op_sel_hi:[1,0,1]
	v_pk_fma_f32 v[54:55], v[42:43], v[28:29], v[54:55] op_sel_hi:[1,0,1]
	v_pk_fma_f32 v[48:49], v[40:41], v[28:29], v[48:49] op_sel_hi:[1,0,1]
	v_pk_fma_f32 v[58:59], v[42:43], v[32:33], v[58:59] op_sel_hi:[1,0,1]
	v_pk_fma_f32 v[52:53], v[40:41], v[32:33], v[52:53] op_sel_hi:[1,0,1]
	v_pk_fma_f32 v[62:63], v[42:43], v[36:37], v[62:63] op_sel_hi:[1,0,1]
	v_pk_fma_f32 v[56:57], v[40:41], v[36:37], v[56:57] op_sel_hi:[1,0,1]
	v_pk_fma_f32 v[66:67], v[42:43], v[12:13], v[66:67] op_sel_hi:[1,0,1]
	v_pk_fma_f32 v[60:61], v[40:41], v[12:13], v[60:61] op_sel_hi:[1,0,1]
	v_pk_fma_f32 v[70:71], v[42:43], v[4:5], v[70:71] op_sel_hi:[1,0,1]
	v_pk_fma_f32 v[64:65], v[40:41], v[4:5], v[64:65] op_sel_hi:[1,0,1]
	s_nop 0
	s_nop 0
	s_nop 0
	s_mov_b32 s13, 0x2a000
	s_waitcnt vmcnt(2)
; #define LAS __attribute__((address_space(3)))
; __device__ __forceinline__ void mod_item(const Params& p, LAS unsigned char* lds, int item, int tid, int wave, int lane) {
;     ...
;         for (int u = 0; u < 8; ++u)
; #pragma unroll
;             for (int r = 0; r < 9; ++r) { const float s = sv[r * 1024 + wave * 128 + k8 + u]; acc[r] += wv[u] * s; }
;     }
; #pragma unroll
;     for (int r = 0; r < 9; ++r) *(LAS f32x4*)(part + (wave * 9 + r) * 256 + 4 * lane) = acc[r];
;     __syncthreads();
;     float* mod = (float*)(p.ws + WS_MOD) + (size_t)l * 9 * NMOD;
;     for (int i = tid; i < 9 * 256; i += NTHR) { const int r = i >> 8, j = i & 255; float s = p.in[I_BMOD][l * NMOD + j0 + j];
; #pragma unroll
;         for (int w = 0; w < 8; ++w) s += part[(w * 9 + r) * 256 + j];
;         mod[r * NMOD + j0 + j] = s; }
	v_mov_b32_e32 v40, v190
	v_mov_b32_e32 v41, v191
	v_mov_b32_e32 v42, v192
	v_mov_b32_e32 v43, v193
	v_pk_fma_f32 v[68:69], v[42:43], v[16:17], v[68:69] op_sel:[0,1,0]
	v_pk_fma_f32 v[46:47], v[40:41], v[16:17], v[46:47] op_sel:[0,1,0]
	v_pk_fma_f32 v[72:73], v[42:43], v[20:21], v[72:73] op_sel:[0,1,0]
	v_pk_fma_f32 v[50:51], v[40:41], v[20:21], v[50:51] op_sel:[0,1,0]
	v_pk_fma_f32 v[74:75], v[42:43], v[24:25], v[74:75] op_sel:[0,1,0]
	v_pk_fma_f32 v[44:45], v[40:41], v[24:25], v[44:45] op_sel:[0,1,0]
	v_pk_fma_f32 v[54:55], v[42:43], v[28:29], v[54:55] op_sel:[0,1,0]
	v_pk_fma_f32 v[48:49], v[40:41], v[28:29], v[48:49] op_sel:[0,1,0]
	v_pk_fma_f32 v[58:59], v[42:43], v[32:33], v[58:59] op_sel:[0,1,0]
	v_pk_fma_f32 v[52:53], v[40:41], v[32:33], v[52:53] op_sel:[0,1,0]
	v_pk_fma_f32 v[86:87], v[42:43], v[36:37], v[62:63] op_sel:[0,1,0]
	v_pk_fma_f32 v[56:57], v[40:41], v[36:37], v[56:57] op_sel:[0,1,0]
	v_pk_fma_f32 v[66:67], v[42:43], v[12:13], v[66:67] op_sel:[0,1,0]
	v_pk_fma_f32 v[12:13], v[40:41], v[12:13], v[60:61] op_sel:[0,1,0]
	v_pk_fma_f32 v[60:61], v[42:43], v[4:5], v[70:71] op_sel:[0,1,0]
	v_pk_fma_f32 v[62:63], v[40:41], v[4:5], v[64:65] op_sel:[0,1,0]
	v_pk_fma_f32 v[4:5], v[42:43], v[0:1], v[82:83] op_sel:[0,1,0]
	v_pk_fma_f32 v[0:1], v[40:41], v[0:1], v[84:85] op_sel:[0,1,0]
	s_waitcnt vmcnt(1)
	v_mov_b32_e32 v8, v194
	v_mov_b32_e32 v9, v195
	v_mov_b32_e32 v10, v196
	v_mov_b32_e32 v11, v197
	v_pk_fma_f32 v[16:17], v[10:11], v[18:19], v[68:69] op_sel_hi:[1,0,1]
	v_pk_fma_f32 v[20:21], v[8:9], v[18:19], v[46:47] op_sel_hi:[1,0,1]
	v_mov_b32_e32 v28, v19
	v_pk_fma_f32 v[18:19], v[10:11], v[22:23], v[72:73] op_sel_hi:[1,0,1]
	v_pk_fma_f32 v[24:25], v[8:9], v[22:23], v[50:51] op_sel_hi:[1,0,1]
	v_mov_b32_e32 v36, v23
	v_pk_fma_f32 v[22:23], v[10:11], v[26:27], v[74:75] op_sel_hi:[1,0,1]
	v_pk_fma_f32 v[32:33], v[8:9], v[26:27], v[44:45] op_sel_hi:[1,0,1]
	v_mov_b32_e32 v42, v27
	v_pk_fma_f32 v[26:27], v[10:11], v[30:31], v[54:55] op_sel_hi:[1,0,1]
	v_pk_fma_f32 v[40:41], v[8:9], v[30:31], v[48:49] op_sel_hi:[1,0,1]
	v_add_co_u32_e32 v30, vcc, s13, v80
	v_mov_b32_e32 v48, v31
	s_nop 0
	v_addc_co_u32_e32 v31, vcc, 0, v81, vcc
	v_pk_fma_f32 v[44:45], v[10:11], v[34:35], v[58:59] op_sel_hi:[1,0,1]
	v_pk_fma_f32 v[58:59], v[10:11], v[14:15], v[66:67] op_sel_hi:[1,0,1]
	v_pk_fma_f32 v[64:65], v[8:9], v[14:15], v[12:13] op_sel_hi:[1,0,1]
	v_mov_b32_e32 v68, v15
	s_nop 0
	v_pk_fma_f32 v[46:47], v[8:9], v[34:35], v[52:53] op_sel_hi:[1,0,1]
	v_mov_b32_e32 v54, v35
	v_pk_fma_f32 v[50:51], v[10:11], v[38:39], v[86:87] op_sel_hi:[1,0,1]
	v_pk_fma_f32 v[52:53], v[8:9], v[38:39], v[56:57] op_sel_hi:[1,0,1]
	v_mov_b32_e32 v56, v39
	v_pk_fma_f32 v[70:71], v[10:11], v[6:7], v[60:61] op_sel_hi:[1,0,1]
	v_pk_fma_f32 v[72:73], v[8:9], v[6:7], v[62:63] op_sel_hi:[1,0,1]
	v_mov_b32_e32 v74, v7
	v_mov_b32_e32 v82, v3
	v_pk_fma_f32 v[10:11], v[10:11], v[2:3], v[4:5] op_sel_hi:[1,0,1]
	v_pk_fma_f32 v[8:9], v[8:9], v[2:3], v[0:1] op_sel_hi:[1,0,1]
	v_lshl_add_u64 v[80:81], v[80:81], 0, s[14:15]
	s_waitcnt vmcnt(0)
	v_mov_b32_e32 v12, v198
	v_mov_b32_e32 v13, v199
	v_mov_b32_e32 v14, v200
	v_mov_b32_e32 v15, v201
	v_pk_fma_f32 v[2:3], v[14:15], v[28:29], v[16:17] op_sel_hi:[1,0,1]
	v_pk_fma_f32 v[0:1], v[12:13], v[28:29], v[20:21] op_sel_hi:[1,0,1]
	v_pk_fma_f32 v[6:7], v[14:15], v[36:37], v[18:19] op_sel_hi:[1,0,1]
	v_pk_fma_f32 v[4:5], v[12:13], v[36:37], v[24:25] op_sel_hi:[1,0,1]
	v_pk_fma_f32 v[30:31], v[14:15], v[42:43], v[22:23] op_sel_hi:[1,0,1]
	v_pk_fma_f32 v[28:29], v[12:13], v[42:43], v[32:33] op_sel_hi:[1,0,1]
	v_pk_fma_f32 v[34:35], v[14:15], v[48:49], v[26:27] op_sel_hi:[1,0,1]
	v_pk_fma_f32 v[32:33], v[12:13], v[48:49], v[40:41] op_sel_hi:[1,0,1]
	v_pk_fma_f32 v[38:39], v[14:15], v[54:55], v[44:45] op_sel_hi:[1,0,1]
	v_pk_fma_f32 v[36:37], v[12:13], v[54:55], v[46:47] op_sel_hi:[1,0,1]
	v_pk_fma_f32 v[62:63], v[14:15], v[56:57], v[50:51] op_sel_hi:[1,0,1]
	v_pk_fma_f32 v[60:61], v[12:13], v[56:57], v[52:53] op_sel_hi:[1,0,1]
	v_pk_fma_f32 v[66:67], v[14:15], v[68:69], v[58:59] op_sel_hi:[1,0,1]
	v_pk_fma_f32 v[64:65], v[12:13], v[68:69], v[64:65] op_sel_hi:[1,0,1]
	v_pk_fma_f32 v[70:71], v[14:15], v[74:75], v[70:71] op_sel_hi:[1,0,1]
	v_pk_fma_f32 v[68:69], v[12:13], v[74:75], v[72:73] op_sel_hi:[1,0,1]
	v_pk_fma_f32 v[74:75], v[14:15], v[82:83], v[10:11] op_sel_hi:[1,0,1]
	v_pk_fma_f32 v[72:73], v[12:13], v[82:83], v[8:9] op_sel_hi:[1,0,1]
	s_cbranch_scc0 .LBB0_374
	ds_write_b128 v117, v[0:3] offset:36864
	ds_write_b128 v117, v[4:7] offset:37888
	ds_write_b128 v117, v[28:31] offset:38912
	ds_write_b128 v117, v[32:35] offset:39936
	ds_write_b128 v117, v[36:39] offset:40960
	ds_write_b128 v117, v[60:63] offset:41984
	ds_write_b128 v117, v[64:67] offset:43008
	ds_write_b128 v117, v[68:71] offset:44032
	ds_write_b128 v117, v[72:75] offset:45056
	s_waitcnt lgkmcnt(0)
	s_barrier
	s_and_saveexec_b64 s[12:13], s[6:7]
	s_cbranch_execz .LBB0_369
	s_mul_i32 s14, s18, 0x36000
	s_mul_hi_i32 s11, s18, 0x36000
	s_add_u32 s14, s73, s14
	s_addc_u32 s15, s57, s11
	s_mul_i32 s11, s18, 0x1800
	s_add_i32 s11, s11, s10
	v_or_b32_e32 v0, s11, v114
	v_ashrrev_i32_e32 v1, 31, v0
	v_lshl_add_u64 v[0:1], v[0:1], 2, s[8:9]
	v_or_b32_e32 v2, s10, v114
	s_mov_b64 s[10:11], 0
	v_mov_b32_e32 v3, v166

; __device__ __forceinline__ void transpose_item(const float* W, int ldw, bf16_t* WT, int ldt, int kofs, int nblk, LAS float* scr, int item, int lane) {
;     ...
; #pragma unroll 8
;     for (int i = 0; i < 32; ++i) { const int kk = 2 * i + (lane >> 5); scr[kk * 33 + (lane & 31)] = W[(size_t)(k0 + kk) * ldw + n0 + (lane & 31)]; }
.LBB0_409:
	s_lshl_b32 s30, s25, 1
	s_lshl_b32 s33, s26, 1
	v_or_b32_e32 v156, s33, v10
	s_add_i32 s53, s30, 4
	s_add_i32 s61, s33, 4
	v_mov_b32_e32 v17, v157
	s_add_i32 s63, s33, 8
	v_lshlrev_b64 v[30:31], 12, v[156:157]
	v_or_b32_e32 v16, s53, v3
	v_or_b32_e32 v156, s61, v10
	v_mov_b32_e32 v15, v157
	v_or_b32_e32 v14, s30, v3
	s_add_i32 s65, s33, 12
	v_lshlrev_b64 v[16:17], 12, v[16:17]
	v_lshlrev_b64 v[32:33], 12, v[156:157]
	v_or_b32_e32 v156, s63, v10
	s_add_i32 s62, s30, 8
	s_add_i32 s64, s30, 12
	s_add_i32 s69, s33, 16
	v_lshlrev_b64 v[14:15], 12, v[14:15]
	v_lshl_add_u64 v[30:31], v[8:9], 0, v[30:31]
	v_lshl_add_u64 v[16:17], v[8:9], 0, v[16:17]
	v_lshlrev_b64 v[34:35], 12, v[156:157]
	v_or_b32_e32 v156, s65, v10
	v_mov_b32_e32 v19, v157
	v_mov_b32_e32 v21, v157
	s_add_i32 s71, s33, 20
	v_or_b32_e32 v18, s62, v3
	v_or_b32_e32 v20, s64, v3
	v_lshl_add_u64 v[14:15], v[8:9], 0, v[14:15]
	v_lshl_add_u64 v[32:33], v[8:9], 0, v[32:33]
	global_load_dword v46, v[30:31], off nt
	global_load_dword v47, v[14:15], off nt
	global_load_dword v48, v[32:33], off nt
	global_load_dword v49, v[16:17], off nt
	v_lshlrev_b64 v[16:17], 12, v[156:157]
	v_or_b32_e32 v156, s69, v10
	s_add_i32 s68, s30, 16
	s_add_i32 s70, s30, 20
	s_add_i32 s75, s33, 24
	v_lshlrev_b64 v[18:19], 12, v[18:19]
	v_lshlrev_b64 v[20:21], 12, v[20:21]
	v_lshl_add_u64 v[14:15], v[8:9], 0, v[34:35]
	v_lshl_add_u64 v[16:17], v[8:9], 0, v[16:17]
	v_lshlrev_b64 v[30:31], 12, v[156:157]
	v_or_b32_e32 v156, s71, v10
	v_mov_b32_e32 v23, v157
	v_mov_b32_e32 v25, v157
	s_add_i32 s74, s30, 24
	s_add_i32 s76, s30, 28
	s_add_i32 s77, s33, 28
	v_or_b32_e32 v22, s68, v3
	v_or_b32_e32 v24, s70, v3
	v_lshl_add_u64 v[18:19], v[8:9], 0, v[18:19]
	v_lshl_add_u64 v[20:21], v[8:9], 0, v[20:21]
	global_load_dword v50, v[14:15], off nt
	global_load_dword v51, v[18:19], off nt
	global_load_dword v52, v[16:17], off nt
	global_load_dword v53, v[20:21], off nt
	v_lshlrev_b64 v[16:17], 12, v[156:157]
	v_or_b32_e32 v156, s75, v10
	v_mov_b32_e32 v27, v157
	v_mov_b32_e32 v29, v157
	v_or_b32_e32 v26, s74, v3
	v_or_b32_e32 v28, s76, v3
	v_lshlrev_b64 v[22:23], 12, v[22:23]
	v_lshlrev_b64 v[24:25], 12, v[24:25]
	v_lshl_add_u64 v[14:15], v[8:9], 0, v[30:31]
	v_lshl_add_u64 v[16:17], v[8:9], 0, v[16:17]
	v_lshlrev_b64 v[18:19], 12, v[156:157]
	v_or_b32_e32 v156, s77, v10
	v_lshlrev_b64 v[26:27], 12, v[26:27]
	v_lshlrev_b64 v[28:29], 12, v[28:29]
	v_lshl_add_u64 v[22:23], v[8:9], 0, v[22:23]
	v_lshl_add_u64 v[24:25], v[8:9], 0, v[24:25]
	global_load_dword v54, v[14:15], off nt
	global_load_dword v55, v[22:23], off nt
	global_load_dword v56, v[16:17], off nt
	global_load_dword v57, v[24:25], off nt
	v_lshl_add_u64 v[14:15], v[8:9], 0, v[18:19]
	v_lshlrev_b64 v[16:17], 12, v[156:157]
	v_lshl_add_u64 v[26:27], v[8:9], 0, v[26:27]
	v_lshl_add_u64 v[28:29], v[8:9], 0, v[28:29]
	v_lshl_add_u64 v[16:17], v[8:9], 0, v[16:17]
	global_load_dword v58, v[14:15], off nt
	global_load_dword v59, v[26:27], off nt
	global_load_dword v60, v[16:17], off nt
	global_load_dword v61, v[28:29], off nt
	v_or_b32_e32 v16, s30, v1
	v_or_b32_e32 v14, s33, v0
	s_add_i32 s26, s26, 16
	s_add_i32 s25, s25, 16
	s_add_i32 s27, s27, -16
	v_mad_u64_u32 v[14:15], s[34:35], v14, s60, v[4:5]
	v_mad_u64_u32 v[16:17], s[34:35], v16, s60, v[4:5]
	v_or_b32_e32 v15, s53, v1
	v_or_b32_e32 v17, s61, v0
	v_or_b32_e32 v24, s62, v1
	v_or_b32_e32 v22, s63, v0
	v_or_b32_e32 v28, s64, v1
	v_or_b32_e32 v26, s65, v0
	v_or_b32_e32 v32, s68, v1
	v_or_b32_e32 v30, s69, v0
	v_or_b32_e32 v36, s70, v1
	v_or_b32_e32 v34, s71, v0
	v_or_b32_e32 v40, s74, v1
	v_or_b32_e32 v38, s75, v0
	v_or_b32_e32 v44, s76, v1
	v_or_b32_e32 v42, s77, v0
	s_cmp_lg_u32 s27, 0
	v_mad_u64_u32 v[18:19], s[34:35], v17, s60, v[4:5]
	v_mad_u64_u32 v[20:21], s[34:35], v15, s60, v[4:5]
	v_mad_u64_u32 v[22:23], s[34:35], v22, s60, v[4:5]
	v_mad_u64_u32 v[24:25], s[34:35], v24, s60, v[4:5]
	v_mad_u64_u32 v[26:27], s[34:35], v26, s60, v[4:5]
	v_mad_u64_u32 v[28:29], s[34:35], v28, s60, v[4:5]
	v_mad_u64_u32 v[30:31], s[34:35], v30, s60, v[4:5]
	v_mad_u64_u32 v[32:33], s[34:35], v32, s60, v[4:5]
	v_mad_u64_u32 v[34:35], s[34:35], v34, s60, v[4:5]
	v_mad_u64_u32 v[36:37], s[34:35], v36, s60, v[4:5]
	v_mad_u64_u32 v[38:39], s[34:35], v38, s60, v[4:5]
	v_mad_u64_u32 v[40:41], s[34:35], v40, s60, v[4:5]
	v_mad_u64_u32 v[42:43], s[34:35], v42, s60, v[4:5]
	v_mad_u64_u32 v[44:45], s[34:35], v44, s60, v[4:5]
	s_waitcnt vmcnt(15)
	ds_write_b32 v14, v46
	s_waitcnt vmcnt(14)
	ds_write_b32 v16, v47
	s_waitcnt vmcnt(13)
	ds_write_b32 v18, v48
	s_waitcnt vmcnt(12)
	ds_write_b32 v20, v49
	s_waitcnt vmcnt(11)
	ds_write_b32 v22, v50
	s_waitcnt vmcnt(10)
	ds_write_b32 v24, v51
	s_waitcnt vmcnt(9)
	ds_write_b32 v26, v52
	s_waitcnt vmcnt(8)
	ds_write_b32 v28, v53
	s_waitcnt vmcnt(7)
	ds_write_b32 v30, v54
	s_waitcnt vmcnt(6)
	ds_write_b32 v32, v55
	s_waitcnt vmcnt(5)
	ds_write_b32 v34, v56
	s_waitcnt vmcnt(4)
	ds_write_b32 v36, v57
	s_waitcnt vmcnt(3)
	ds_write_b32 v38, v58
	s_waitcnt vmcnt(2)
	ds_write_b32 v40, v59
	s_waitcnt vmcnt(1)
	ds_write_b32 v42, v60
	s_waitcnt vmcnt(0)
	ds_write_b32 v44, v61
	s_cbranch_scc1 .LBB0_409
; #define LAS __attribute__((address_space(3)))
; __device__ __forceinline__ unsigned cvt_pk_bf16(float lo, float hi) { const f32x2 v = (f32x2){lo, hi}; return __builtin_bit_cast(unsigned, __builtin_convertvector(v, bf16v2)); }
; #define LDS_WAIT() asm volatile("s_waitcnt lgkmcnt(0)" ::: "memory")
; __device__ __forceinline__ void transpose_item(const float* W, int ldw, bf16_t* WT, int ldt, int kofs, int nblk, LAS float* scr, int item, int lane) {
;     ...
;     const int c = lane & 7;
; #pragma unroll
;     for (int j = 0; j < 4; ++j) { const int n = (lane >> 3) + 8 * j; const LAS float* s = scr + (8 * c) * 33 + n;
;         u32x4 o; o.x = cvt_pk_bf16(s[0 * 33], s[1 * 33]); o.y = cvt_pk_bf16(s[2 * 33], s[3 * 33]); o.z = cvt_pk_bf16(s[4 * 33], s[5 * 33]); o.w = cvt_pk_bf16(s[6 * 33], s[7 * 33]);
;         *(u32x4*)(WT + (size_t)(n0 + n) * ldt + kofs + k0 + 8 * c) = o; }
;     LDS_WAIT(); asm volatile("" ::: "memory");
	s_waitcnt lgkmcnt(0)
	s_add_u32 s25, s17, s4
	ds_read2_b32 v[8:9], v7 offset0:33 offset1:41
	ds_read2_b32 v[18:19], v7 offset1:8
	ds_read2_b32 v[20:21], v7 offset0:66 offset1:74
	ds_read2_b32 v[22:23], v7 offset0:99 offset1:107
	ds_read2_b32 v[24:25], v7 offset0:132 offset1:140
	ds_read2_b32 v[26:27], v7 offset0:165 offset1:173
	ds_read2_b32 v[28:29], v7 offset0:198 offset1:206
	ds_read2_b32 v[30:31], v7 offset0:231 offset1:239
	s_addc_u32 s27, s18, s5
	s_lshl_b32 s9, s9, 1
	s_add_u32 s26, s25, s9
	s_addc_u32 s27, s27, 0
	v_lshlrev_b32_e32 v156, 1, v6
	v_or_b32_e32 v3, s8, v5
	v_lshl_add_u64 v[32:33], s[26:27], 0, v[156:157]
	v_lshlrev_b32_e32 v156, 13, v3
	s_waitcnt lgkmcnt(6)
	v_cvt_pk_bf16_f32 v14, v18, v8
	s_waitcnt lgkmcnt(4)
	v_cvt_pk_bf16_f32 v15, v20, v22
	s_waitcnt lgkmcnt(2)
	v_cvt_pk_bf16_f32 v16, v24, v26
	s_waitcnt lgkmcnt(0)
	v_cvt_pk_bf16_f32 v17, v28, v30
	v_lshl_add_u64 v[34:35], v[32:33], 0, v[156:157]
	global_store_dwordx4 v[34:35], v[14:17], off
	v_or_b32_e32 v3, s8, v11
	v_lshlrev_b32_e32 v156, 13, v3
	v_cvt_pk_bf16_f32 v14, v19, v9
	v_cvt_pk_bf16_f32 v15, v21, v23
	v_cvt_pk_bf16_f32 v16, v25, v27
	v_cvt_pk_bf16_f32 v17, v29, v31
	ds_read2_b32 v[18:19], v7 offset0:49 offset1:57
	ds_read2_b32 v[20:21], v7 offset0:16 offset1:24
	ds_read2_b32 v[22:23], v7 offset0:82 offset1:90
	ds_read2_b32 v[24:25], v7 offset0:115 offset1:123
	ds_read2_b32 v[26:27], v7 offset0:148 offset1:156
	ds_read2_b32 v[28:29], v7 offset0:181 offset1:189
	ds_read2_b32 v[30:31], v7 offset0:214 offset1:222
	ds_read2_b32 v[34:35], v7 offset0:247 offset1:255
	v_or_b32_e32 v3, s8, v12
	v_lshl_add_u64 v[8:9], v[32:33], 0, v[156:157]
	v_lshlrev_b32_e32 v156, 13, v3
	v_or_b32_e32 v3, s8, v13
	global_store_dwordx4 v[8:9], v[14:17], off
	v_lshl_add_u64 v[8:9], v[32:33], 0, v[156:157]
	v_lshlrev_b32_e32 v156, 13, v3
	s_waitcnt lgkmcnt(6)
	v_cvt_pk_bf16_f32 v14, v20, v18
	s_waitcnt lgkmcnt(4)
	v_cvt_pk_bf16_f32 v15, v22, v24
	s_waitcnt lgkmcnt(2)
	v_cvt_pk_bf16_f32 v16, v26, v28
	s_waitcnt lgkmcnt(0)
	v_cvt_pk_bf16_f32 v17, v30, v34
	global_store_dwordx4 v[8:9], v[14:17], off
	v_lshl_add_u64 v[8:9], v[32:33], 0, v[156:157]
	s_mov_b64 s[8:9], 0
	v_cvt_pk_bf16_f32 v14, v21, v19
	v_cvt_pk_bf16_f32 v15, v23, v25
	v_cvt_pk_bf16_f32 v16, v27, v29
	v_cvt_pk_bf16_f32 v17, v31, v35
	global_store_dwordx4 v[8:9], v[14:17], off
	s_waitcnt lgkmcnt(0)

; __device__ __forceinline__ void transpose_item(const float* W, int ldw, bf16_t* WT, int ldt, int kofs, int nblk, LAS float* scr, int item, int lane) {
;     ...
; #pragma unroll 8
;     for (int i = 0; i < 32; ++i) { const int kk = 2 * i + (lane >> 5); scr[kk * 33 + (lane & 31)] = W[(size_t)(k0 + kk) * ldw + n0 + (lane & 31)]; }
.LBB0_413:
	s_lshl_b32 s25, s8, 1
	s_lshl_b32 s26, s9, 1
	v_or_b32_e32 v156, s26, v10
	s_add_i32 s30, s25, 4
	s_add_i32 s33, s26, 4
	v_mov_b32_e32 v17, v157
	s_add_i32 s35, s26, 8
	v_lshlrev_b64 v[30:31], 14, v[156:157]
	v_or_b32_e32 v16, s30, v3
	v_or_b32_e32 v156, s33, v10
	v_mov_b32_e32 v15, v157
	v_or_b32_e32 v14, s25, v3
	s_add_i32 s61, s26, 12
	v_lshlrev_b64 v[16:17], 14, v[16:17]
	v_lshlrev_b64 v[32:33], 14, v[156:157]
	v_or_b32_e32 v156, s35, v10
	s_add_i32 s34, s25, 8
	s_add_i32 s53, s25, 12
	s_add_i32 s63, s26, 16
	v_lshlrev_b64 v[14:15], 14, v[14:15]
	v_lshl_add_u64 v[30:31], v[8:9], 0, v[30:31]
	v_lshl_add_u64 v[16:17], v[8:9], 0, v[16:17]
	v_lshlrev_b64 v[34:35], 14, v[156:157]
	v_or_b32_e32 v156, s61, v10
	v_mov_b32_e32 v19, v157
	v_mov_b32_e32 v21, v157
	s_add_i32 s65, s26, 20
	v_or_b32_e32 v18, s34, v3
	v_or_b32_e32 v20, s53, v3
	v_lshl_add_u64 v[14:15], v[8:9], 0, v[14:15]
	v_lshl_add_u64 v[32:33], v[8:9], 0, v[32:33]
	global_load_dword v46, v[30:31], off nt
	global_load_dword v47, v[14:15], off nt
	global_load_dword v48, v[32:33], off nt
	global_load_dword v49, v[16:17], off nt
	v_lshlrev_b64 v[16:17], 14, v[156:157]
	v_or_b32_e32 v156, s63, v10
	s_add_i32 s62, s25, 16
	s_add_i32 s64, s25, 20
	s_add_i32 s69, s26, 24
	v_lshlrev_b64 v[18:19], 14, v[18:19]
	v_lshlrev_b64 v[20:21], 14, v[20:21]
	v_lshl_add_u64 v[14:15], v[8:9], 0, v[34:35]
	v_lshl_add_u64 v[16:17], v[8:9], 0, v[16:17]
	v_lshlrev_b64 v[30:31], 14, v[156:157]
	v_or_b32_e32 v156, s65, v10
	v_mov_b32_e32 v23, v157
	v_mov_b32_e32 v25, v157
	s_add_i32 s68, s25, 24
	s_add_i32 s70, s25, 28
	s_add_i32 s71, s26, 28
	v_or_b32_e32 v22, s62, v3
	v_or_b32_e32 v24, s64, v3
	v_lshl_add_u64 v[18:19], v[8:9], 0, v[18:19]
	v_lshl_add_u64 v[20:21], v[8:9], 0, v[20:21]
	global_load_dword v50, v[14:15], off nt
	global_load_dword v51, v[18:19], off nt
	global_load_dword v52, v[16:17], off nt
	global_load_dword v53, v[20:21], off nt
	v_lshlrev_b64 v[16:17], 14, v[156:157]
	v_or_b32_e32 v156, s69, v10
	v_mov_b32_e32 v27, v157
	v_mov_b32_e32 v29, v157
	v_or_b32_e32 v26, s68, v3
	v_or_b32_e32 v28, s70, v3
	v_lshlrev_b64 v[22:23], 14, v[22:23]
	v_lshlrev_b64 v[24:25], 14, v[24:25]
	v_lshl_add_u64 v[14:15], v[8:9], 0, v[30:31]
	v_lshl_add_u64 v[16:17], v[8:9], 0, v[16:17]
	v_lshlrev_b64 v[18:19], 14, v[156:157]
	v_or_b32_e32 v156, s71, v10
	v_lshlrev_b64 v[26:27], 14, v[26:27]
	v_lshlrev_b64 v[28:29], 14, v[28:29]
	v_lshl_add_u64 v[22:23], v[8:9], 0, v[22:23]
	v_lshl_add_u64 v[24:25], v[8:9], 0, v[24:25]
	global_load_dword v54, v[14:15], off nt
	global_load_dword v55, v[22:23], off nt
	global_load_dword v56, v[16:17], off nt
	global_load_dword v57, v[24:25], off nt
	v_lshl_add_u64 v[14:15], v[8:9], 0, v[18:19]
	v_lshlrev_b64 v[16:17], 14, v[156:157]
	v_lshl_add_u64 v[26:27], v[8:9], 0, v[26:27]
	v_lshl_add_u64 v[28:29], v[8:9], 0, v[28:29]
	v_lshl_add_u64 v[16:17], v[8:9], 0, v[16:17]
	global_load_dword v58, v[14:15], off nt
	global_load_dword v59, v[26:27], off nt
	global_load_dword v60, v[16:17], off nt
	global_load_dword v61, v[28:29], off nt
	v_or_b32_e32 v16, s25, v1
	v_or_b32_e32 v14, s26, v0
	s_add_i32 s9, s9, 16
	s_add_i32 s8, s8, 16
	s_add_i32 s24, s24, -16
	v_mad_u64_u32 v[14:15], s[26:27], v14, s60, v[4:5]
	v_mad_u64_u32 v[16:17], s[26:27], v16, s60, v[4:5]
	v_or_b32_e32 v15, s30, v1
	v_or_b32_e32 v17, s33, v0
	v_or_b32_e32 v24, s34, v1
	v_or_b32_e32 v22, s35, v0
	v_or_b32_e32 v28, s53, v1
	v_or_b32_e32 v26, s61, v0
	v_or_b32_e32 v32, s62, v1
	v_or_b32_e32 v30, s63, v0
	v_or_b32_e32 v36, s64, v1
	v_or_b32_e32 v34, s65, v0
	v_or_b32_e32 v40, s68, v1
	v_or_b32_e32 v38, s69, v0
	v_or_b32_e32 v44, s70, v1
	v_or_b32_e32 v42, s71, v0
	s_cmp_lg_u32 s24, 0
	v_mad_u64_u32 v[18:19], s[26:27], v17, s60, v[4:5]
	v_mad_u64_u32 v[20:21], s[26:27], v15, s60, v[4:5]
	v_mad_u64_u32 v[22:23], s[26:27], v22, s60, v[4:5]
	v_mad_u64_u32 v[24:25], s[26:27], v24, s60, v[4:5]
	v_mad_u64_u32 v[26:27], s[26:27], v26, s60, v[4:5]
	v_mad_u64_u32 v[28:29], s[26:27], v28, s60, v[4:5]
	v_mad_u64_u32 v[30:31], s[26:27], v30, s60, v[4:5]
	v_mad_u64_u32 v[32:33], s[26:27], v32, s60, v[4:5]
	v_mad_u64_u32 v[34:35], s[26:27], v34, s60, v[4:5]
	v_mad_u64_u32 v[36:37], s[26:27], v36, s60, v[4:5]
	v_mad_u64_u32 v[38:39], s[26:27], v38, s60, v[4:5]
	v_mad_u64_u32 v[40:41], s[26:27], v40, s60, v[4:5]
	v_mad_u64_u32 v[42:43], s[26:27], v42, s60, v[4:5]
	v_mad_u64_u32 v[44:45], s[26:27], v44, s60, v[4:5]
	s_waitcnt vmcnt(15)
	ds_write_b32 v14, v46
	s_waitcnt vmcnt(14)
	ds_write_b32 v16, v47
	s_waitcnt vmcnt(13)
	ds_write_b32 v18, v48
	s_waitcnt vmcnt(12)
	ds_write_b32 v20, v49
	s_waitcnt vmcnt(11)
	ds_write_b32 v22, v50
	s_waitcnt vmcnt(10)
	ds_write_b32 v24, v51
	s_waitcnt vmcnt(9)
	ds_write_b32 v26, v52
	s_waitcnt vmcnt(8)
	ds_write_b32 v28, v53
	s_waitcnt vmcnt(7)
	ds_write_b32 v30, v54
	s_waitcnt vmcnt(6)
	ds_write_b32 v32, v55
	s_waitcnt vmcnt(5)
	ds_write_b32 v34, v56
	s_waitcnt vmcnt(4)
	ds_write_b32 v36, v57
	s_waitcnt vmcnt(3)
	ds_write_b32 v38, v58
	s_waitcnt vmcnt(2)
	ds_write_b32 v40, v59
	s_waitcnt vmcnt(1)
	ds_write_b32 v42, v60
	s_waitcnt vmcnt(0)
	ds_write_b32 v44, v61
	s_cbranch_scc1 .LBB0_413
; #define LAS __attribute__((address_space(3)))
; __device__ __forceinline__ unsigned cvt_pk_bf16(float lo, float hi) { const f32x2 v = (f32x2){lo, hi}; return __builtin_bit_cast(unsigned, __builtin_convertvector(v, bf16v2)); }
; #define LDS_WAIT() asm volatile("s_waitcnt lgkmcnt(0)" ::: "memory")
; __device__ __forceinline__ void transpose_item(const float* W, int ldw, bf16_t* WT, int ldt, int kofs, int nblk, LAS float* scr, int item, int lane) {
;     ...
;     const int c = lane & 7;
; #pragma unroll
;     for (int j = 0; j < 4; ++j) { const int n = (lane >> 3) + 8 * j; const LAS float* s = scr + (8 * c) * 33 + n;
;         u32x4 o; o.x = cvt_pk_bf16(s[0 * 33], s[1 * 33]); o.y = cvt_pk_bf16(s[2 * 33], s[3 * 33]); o.z = cvt_pk_bf16(s[4 * 33], s[5 * 33]); o.w = cvt_pk_bf16(s[6 * 33], s[7 * 33]);
;         *(u32x4*)(WT + (size_t)(n0 + n) * ldt + kofs + k0 + 8 * c) = o; }
;     LDS_WAIT(); asm volatile("" ::: "memory");
	s_waitcnt lgkmcnt(0)
	s_add_u32 s4, s19, s4
	ds_read2_b32 v[8:9], v7 offset0:33 offset1:41
	ds_read2_b32 v[18:19], v7 offset1:8
	ds_read2_b32 v[20:21], v7 offset0:66 offset1:74
	ds_read2_b32 v[22:23], v7 offset0:99 offset1:107
	ds_read2_b32 v[24:25], v7 offset0:132 offset1:140
	ds_read2_b32 v[26:27], v7 offset0:165 offset1:173
	ds_read2_b32 v[28:29], v7 offset0:198 offset1:206
	ds_read2_b32 v[30:31], v7 offset0:231 offset1:239
	s_addc_u32 s5, s20, s5
	s_lshl_b32 s7, s7, 1
	s_add_u32 s4, s4, s7
	s_addc_u32 s5, s5, 0
	v_lshlrev_b32_e32 v156, 1, v6
	v_or_b32_e32 v3, s6, v5
	v_lshl_add_u64 v[32:33], s[4:5], 0, v[156:157]
	v_lshlrev_b32_e32 v156, 11, v3
	s_waitcnt lgkmcnt(6)
	v_cvt_pk_bf16_f32 v14, v18, v8
	s_waitcnt lgkmcnt(4)
	v_cvt_pk_bf16_f32 v15, v20, v22
	s_waitcnt lgkmcnt(2)
	v_cvt_pk_bf16_f32 v16, v24, v26
	s_waitcnt lgkmcnt(0)
	v_cvt_pk_bf16_f32 v17, v28, v30
	v_lshl_add_u64 v[34:35], v[32:33], 0, v[156:157]
	global_store_dwordx4 v[34:35], v[14:17], off
	v_or_b32_e32 v3, s6, v11
	v_lshlrev_b32_e32 v156, 11, v3
	v_cvt_pk_bf16_f32 v14, v19, v9
	v_cvt_pk_bf16_f32 v15, v21, v23
	v_cvt_pk_bf16_f32 v16, v25, v27
	v_cvt_pk_bf16_f32 v17, v29, v31
	ds_read2_b32 v[18:19], v7 offset0:49 offset1:57
	ds_read2_b32 v[20:21], v7 offset0:16 offset1:24
	ds_read2_b32 v[22:23], v7 offset0:82 offset1:90
	ds_read2_b32 v[24:25], v7 offset0:115 offset1:123
	ds_read2_b32 v[26:27], v7 offset0:148 offset1:156
	ds_read2_b32 v[28:29], v7 offset0:181 offset1:189
	ds_read2_b32 v[30:31], v7 offset0:214 offset1:222
	ds_read2_b32 v[34:35], v7 offset0:247 offset1:255
	v_or_b32_e32 v3, s6, v12
	v_lshl_add_u64 v[8:9], v[32:33], 0, v[156:157]
	v_lshlrev_b32_e32 v156, 11, v3
	v_or_b32_e32 v3, s6, v13
	global_store_dwordx4 v[8:9], v[14:17], off
	v_lshl_add_u64 v[8:9], v[32:33], 0, v[156:157]
	v_lshlrev_b32_e32 v156, 11, v3
	s_waitcnt lgkmcnt(6)
	v_cvt_pk_bf16_f32 v14, v20, v18
	s_waitcnt lgkmcnt(4)
	v_cvt_pk_bf16_f32 v15, v22, v24
	s_waitcnt lgkmcnt(2)
	v_cvt_pk_bf16_f32 v16, v26, v28
	s_waitcnt lgkmcnt(0)
	v_cvt_pk_bf16_f32 v17, v30, v34
	global_store_dwordx4 v[8:9], v[14:17], off
	v_lshl_add_u64 v[8:9], v[32:33], 0, v[156:157]
	s_nop 0
	v_cvt_pk_bf16_f32 v14, v21, v19
	v_cvt_pk_bf16_f32 v15, v23, v25
	v_cvt_pk_bf16_f32 v16, v27, v29
	v_cvt_pk_bf16_f32 v17, v31, v35
	global_store_dwordx4 v[8:9], v[14:17], off
	s_waitcnt lgkmcnt(0)

; __device__ __forceinline__ void transpose_item(const float* W, int ldw, bf16_t* WT, int ldt, int kofs, int nblk, LAS float* scr, int item, int lane) {
;     ...
; #pragma unroll 8
;     for (int i = 0; i < 32; ++i) { const int kk = 2 * i + (lane >> 5); scr[kk * 33 + (lane & 31)] = W[(size_t)(k0 + kk) * ldw + n0 + (lane & 31)]; }
.LBB0_418:
	s_lshl_b32 s25, s8, 1
	s_lshl_b32 s26, s9, 1
	v_or_b32_e32 v156, s26, v10
	s_add_i32 s30, s25, 4
	s_add_i32 s33, s26, 4
	v_mov_b32_e32 v17, v157
	s_add_i32 s35, s26, 8
	v_lshlrev_b64 v[30:31], 12, v[156:157]
	v_or_b32_e32 v16, s30, v3
	v_or_b32_e32 v156, s33, v10
	v_mov_b32_e32 v15, v157
	v_or_b32_e32 v14, s25, v3
	s_add_i32 s61, s26, 12
	v_lshlrev_b64 v[16:17], 12, v[16:17]
	v_lshlrev_b64 v[32:33], 12, v[156:157]
	v_or_b32_e32 v156, s35, v10
	s_add_i32 s34, s25, 8
	s_add_i32 s53, s25, 12
	s_add_i32 s63, s26, 16
	v_lshlrev_b64 v[14:15], 12, v[14:15]
	v_lshl_add_u64 v[30:31], v[8:9], 0, v[30:31]
	v_lshl_add_u64 v[16:17], v[8:9], 0, v[16:17]
	v_lshlrev_b64 v[34:35], 12, v[156:157]
	v_or_b32_e32 v156, s61, v10
	v_mov_b32_e32 v19, v157
	v_mov_b32_e32 v21, v157
	s_add_i32 s65, s26, 20
	v_or_b32_e32 v18, s34, v3
	v_or_b32_e32 v20, s53, v3
	v_lshl_add_u64 v[14:15], v[8:9], 0, v[14:15]
	v_lshl_add_u64 v[32:33], v[8:9], 0, v[32:33]
	global_load_dword v46, v[30:31], off nt
	global_load_dword v47, v[14:15], off nt
	global_load_dword v48, v[32:33], off nt
	global_load_dword v49, v[16:17], off nt
	v_lshlrev_b64 v[16:17], 12, v[156:157]
	v_or_b32_e32 v156, s63, v10
	s_add_i32 s62, s25, 16
	s_add_i32 s64, s25, 20
	s_add_i32 s69, s26, 24
	v_lshlrev_b64 v[18:19], 12, v[18:19]
	v_lshlrev_b64 v[20:21], 12, v[20:21]
	v_lshl_add_u64 v[14:15], v[8:9], 0, v[34:35]
	v_lshl_add_u64 v[16:17], v[8:9], 0, v[16:17]
	v_lshlrev_b64 v[30:31], 12, v[156:157]
	v_or_b32_e32 v156, s65, v10
	v_mov_b32_e32 v23, v157
	v_mov_b32_e32 v25, v157
	s_add_i32 s68, s25, 24
	s_add_i32 s70, s25, 28
	s_add_i32 s71, s26, 28
	v_or_b32_e32 v22, s62, v3
	v_or_b32_e32 v24, s64, v3
	v_lshl_add_u64 v[18:19], v[8:9], 0, v[18:19]
	v_lshl_add_u64 v[20:21], v[8:9], 0, v[20:21]
	global_load_dword v50, v[14:15], off nt
	global_load_dword v51, v[18:19], off nt
	global_load_dword v52, v[16:17], off nt
	global_load_dword v53, v[20:21], off nt
	v_lshlrev_b64 v[16:17], 12, v[156:157]
	v_or_b32_e32 v156, s69, v10
	v_mov_b32_e32 v27, v157
	v_mov_b32_e32 v29, v157
	v_or_b32_e32 v26, s68, v3
	v_or_b32_e32 v28, s70, v3
	v_lshlrev_b64 v[22:23], 12, v[22:23]
	v_lshlrev_b64 v[24:25], 12, v[24:25]
	v_lshl_add_u64 v[14:15], v[8:9], 0, v[30:31]
	v_lshl_add_u64 v[16:17], v[8:9], 0, v[16:17]
	v_lshlrev_b64 v[18:19], 12, v[156:157]
	v_or_b32_e32 v156, s71, v10
	v_lshlrev_b64 v[26:27], 12, v[26:27]
	v_lshlrev_b64 v[28:29], 12, v[28:29]
	v_lshl_add_u64 v[22:23], v[8:9], 0, v[22:23]
	v_lshl_add_u64 v[24:25], v[8:9], 0, v[24:25]
	global_load_dword v54, v[14:15], off nt
	global_load_dword v55, v[22:23], off nt
	global_load_dword v56, v[16:17], off nt
	global_load_dword v57, v[24:25], off nt
	v_lshl_add_u64 v[14:15], v[8:9], 0, v[18:19]
	v_lshlrev_b64 v[16:17], 12, v[156:157]
	v_lshl_add_u64 v[26:27], v[8:9], 0, v[26:27]
	v_lshl_add_u64 v[28:29], v[8:9], 0, v[28:29]
	v_lshl_add_u64 v[16:17], v[8:9], 0, v[16:17]
	global_load_dword v58, v[14:15], off nt
	global_load_dword v59, v[26:27], off nt
	global_load_dword v60, v[16:17], off nt
	global_load_dword v61, v[28:29], off nt
	v_or_b32_e32 v16, s25, v1
	v_or_b32_e32 v14, s26, v0
	s_add_i32 s9, s9, 16
	s_add_i32 s8, s8, 16
	s_add_i32 s24, s24, -16
	v_mad_u64_u32 v[14:15], s[26:27], v14, s60, v[4:5]
	v_mad_u64_u32 v[16:17], s[26:27], v16, s60, v[4:5]
	v_or_b32_e32 v15, s30, v1
	v_or_b32_e32 v17, s33, v0
	v_or_b32_e32 v24, s34, v1
	v_or_b32_e32 v22, s35, v0
	v_or_b32_e32 v28, s53, v1
	v_or_b32_e32 v26, s61, v0
	v_or_b32_e32 v32, s62, v1
	v_or_b32_e32 v30, s63, v0
	v_or_b32_e32 v36, s64, v1
	v_or_b32_e32 v34, s65, v0
	v_or_b32_e32 v40, s68, v1
	v_or_b32_e32 v38, s69, v0
	v_or_b32_e32 v44, s70, v1
	v_or_b32_e32 v42, s71, v0
	s_cmp_lg_u32 s24, 0
	v_mad_u64_u32 v[18:19], s[26:27], v17, s60, v[4:5]
	v_mad_u64_u32 v[20:21], s[26:27], v15, s60, v[4:5]
	v_mad_u64_u32 v[22:23], s[26:27], v22, s60, v[4:5]
	v_mad_u64_u32 v[24:25], s[26:27], v24, s60, v[4:5]
	v_mad_u64_u32 v[26:27], s[26:27], v26, s60, v[4:5]
	v_mad_u64_u32 v[28:29], s[26:27], v28, s60, v[4:5]
	v_mad_u64_u32 v[30:31], s[26:27], v30, s60, v[4:5]
	v_mad_u64_u32 v[32:33], s[26:27], v32, s60, v[4:5]
	v_mad_u64_u32 v[34:35], s[26:27], v34, s60, v[4:5]
	v_mad_u64_u32 v[36:37], s[26:27], v36, s60, v[4:5]
	v_mad_u64_u32 v[38:39], s[26:27], v38, s60, v[4:5]
	v_mad_u64_u32 v[40:41], s[26:27], v40, s60, v[4:5]
	v_mad_u64_u32 v[42:43], s[26:27], v42, s60, v[4:5]
	v_mad_u64_u32 v[44:45], s[26:27], v44, s60, v[4:5]
	s_waitcnt vmcnt(15)
	ds_write_b32 v14, v46
	s_waitcnt vmcnt(14)
	ds_write_b32 v16, v47
	s_waitcnt vmcnt(13)
	ds_write_b32 v18, v48
	s_waitcnt vmcnt(12)
	ds_write_b32 v20, v49
	s_waitcnt vmcnt(11)
	ds_write_b32 v22, v50
	s_waitcnt vmcnt(10)
	ds_write_b32 v24, v51
	s_waitcnt vmcnt(9)
	ds_write_b32 v26, v52
	s_waitcnt vmcnt(8)
	ds_write_b32 v28, v53
	s_waitcnt vmcnt(7)
	ds_write_b32 v30, v54
	s_waitcnt vmcnt(6)
	ds_write_b32 v32, v55
	s_waitcnt vmcnt(5)
	ds_write_b32 v34, v56
	s_waitcnt vmcnt(4)
	ds_write_b32 v36, v57
	s_waitcnt vmcnt(3)
	ds_write_b32 v38, v58
	s_waitcnt vmcnt(2)
	ds_write_b32 v40, v59
	s_waitcnt vmcnt(1)
	ds_write_b32 v42, v60
	s_waitcnt vmcnt(0)
	ds_write_b32 v44, v61
	s_cbranch_scc1 .LBB0_418
; #define LAS __attribute__((address_space(3)))
; __device__ __forceinline__ unsigned cvt_pk_bf16(float lo, float hi) { const f32x2 v = (f32x2){lo, hi}; return __builtin_bit_cast(unsigned, __builtin_convertvector(v, bf16v2)); }
; #define LDS_WAIT() asm volatile("s_waitcnt lgkmcnt(0)" ::: "memory")
; __device__ __forceinline__ void transpose_item(const float* W, int ldw, bf16_t* WT, int ldt, int kofs, int nblk, LAS float* scr, int item, int lane) {
;     ...
;     const int c = lane & 7;
; #pragma unroll
;     for (int j = 0; j < 4; ++j) { const int n = (lane >> 3) + 8 * j; const LAS float* s = scr + (8 * c) * 33 + n;
;         u32x4 o; o.x = cvt_pk_bf16(s[0 * 33], s[1 * 33]); o.y = cvt_pk_bf16(s[2 * 33], s[3 * 33]); o.z = cvt_pk_bf16(s[4 * 33], s[5 * 33]); o.w = cvt_pk_bf16(s[6 * 33], s[7 * 33]);
;         *(u32x4*)(WT + (size_t)(n0 + n) * ldt + kofs + k0 + 8 * c) = o; }
;     LDS_WAIT(); asm volatile("" ::: "memory");
	s_lshl_b64 s[4:5], s[4:5], 1
	s_waitcnt lgkmcnt(0)
	s_add_u32 s4, s73, s4
	s_addc_u32 s5, s57, s5
	s_lshl_b32 s7, s7, 1
	ds_read2_b32 v[18:19], v7 offset0:33 offset1:41
	ds_read2_b32 v[20:21], v7 offset1:8
	ds_read2_b32 v[22:23], v7 offset0:66 offset1:74
	ds_read2_b32 v[24:25], v7 offset0:99 offset1:107
	ds_read2_b32 v[26:27], v7 offset0:132 offset1:140
	ds_read2_b32 v[28:29], v7 offset0:165 offset1:173
	ds_read2_b32 v[30:31], v7 offset0:198 offset1:206
	ds_read2_b32 v[32:33], v7 offset0:231 offset1:239
	s_add_u32 s4, s4, s7
	s_addc_u32 s5, s5, 0
	v_lshlrev_b32_e32 v156, 1, v6
	v_lshl_add_u64 v[8:9], s[4:5], 0, v[156:157]
	s_mov_b64 s[4:5], 0x1c00400
	v_or_b32_e32 v3, s6, v5
	v_lshl_add_u64 v[8:9], v[8:9], 0, s[4:5]
	v_lshlrev_b32_e32 v156, 11, v3
	s_waitcnt lgkmcnt(6)
	v_cvt_pk_bf16_f32 v14, v20, v18
	s_waitcnt lgkmcnt(4)
	v_cvt_pk_bf16_f32 v15, v22, v24
	s_waitcnt lgkmcnt(2)
	v_cvt_pk_bf16_f32 v16, v26, v28
	s_waitcnt lgkmcnt(0)
	v_cvt_pk_bf16_f32 v17, v30, v32
	v_lshl_add_u64 v[34:35], v[8:9], 0, v[156:157]
	global_store_dwordx4 v[34:35], v[14:17], off
	v_or_b32_e32 v3, s6, v11
	v_lshlrev_b32_e32 v156, 11, v3
	v_cvt_pk_bf16_f32 v14, v21, v19
	v_cvt_pk_bf16_f32 v15, v23, v25
	v_cvt_pk_bf16_f32 v16, v27, v29
	v_cvt_pk_bf16_f32 v17, v31, v33
	ds_read2_b32 v[20:21], v7 offset0:49 offset1:57
	ds_read2_b32 v[22:23], v7 offset0:16 offset1:24
	ds_read2_b32 v[24:25], v7 offset0:82 offset1:90
	ds_read2_b32 v[26:27], v7 offset0:115 offset1:123
	ds_read2_b32 v[28:29], v7 offset0:148 offset1:156
	ds_read2_b32 v[30:31], v7 offset0:181 offset1:189
	ds_read2_b32 v[32:33], v7 offset0:214 offset1:222
	ds_read2_b32 v[34:35], v7 offset0:247 offset1:255
	v_or_b32_e32 v3, s6, v12
	v_lshl_add_u64 v[18:19], v[8:9], 0, v[156:157]
	v_lshlrev_b32_e32 v156, 11, v3
	v_or_b32_e32 v3, s6, v13
	global_store_dwordx4 v[18:19], v[14:17], off
	v_lshl_add_u64 v[18:19], v[8:9], 0, v[156:157]
	v_lshlrev_b32_e32 v156, 11, v3
	s_waitcnt lgkmcnt(6)
	v_cvt_pk_bf16_f32 v14, v22, v20
	s_waitcnt lgkmcnt(4)
	v_cvt_pk_bf16_f32 v15, v24, v26
	s_waitcnt lgkmcnt(2)
	v_cvt_pk_bf16_f32 v16, v28, v30
	s_waitcnt lgkmcnt(0)
	v_cvt_pk_bf16_f32 v17, v32, v34
	global_store_dwordx4 v[18:19], v[14:17], off
	v_lshl_add_u64 v[8:9], v[8:9], 0, v[156:157]
	s_nop 0
	v_cvt_pk_bf16_f32 v14, v23, v21
	v_cvt_pk_bf16_f32 v15, v25, v27
	v_cvt_pk_bf16_f32 v16, v29, v31
	v_cvt_pk_bf16_f32 v17, v33, v35
	global_store_dwordx4 v[8:9], v[14:17], off
	s_waitcnt lgkmcnt(0)

; __device__ __forceinline__ void transpose_item(const float* W, int ldw, bf16_t* WT, int ldt, int kofs, int nblk, LAS float* scr, int item, int lane) {
;     ...
; #pragma unroll 8
;     for (int i = 0; i < 32; ++i) { const int kk = 2 * i + (lane >> 5); scr[kk * 33 + (lane & 31)] = W[(size_t)(k0 + kk) * ldw + n0 + (lane & 31)]; }
.LBB0_422:
	s_lshl_b32 s9, s5, 1
	s_lshl_b32 s23, s7, 1
	v_or_b32_e32 v16, s23, v10
	s_add_i32 s24, s9, 4
	s_add_i32 s25, s23, 4
	s_add_i32 s26, s9, 8
	s_add_i32 s27, s23, 8
	s_add_i32 s30, s9, 12
	s_add_i32 s33, s23, 12
	s_add_i32 s53, s9, 16
	s_add_i32 s61, s23, 16
	s_add_i32 s62, s9, 20
	s_add_i32 s63, s23, 20
	s_add_i32 s64, s9, 24
	s_add_i32 s65, s23, 24
	s_add_i32 s68, s9, 28
	s_add_i32 s69, s23, 28
	v_or_b32_e32 v14, s9, v3
	v_ashrrev_i32_e32 v17, 31, v16
	v_or_b32_e32 v18, s24, v3
	v_or_b32_e32 v20, s25, v10
	v_or_b32_e32 v22, s26, v3
	v_or_b32_e32 v24, s27, v10
	v_or_b32_e32 v26, s30, v3
	v_or_b32_e32 v28, s33, v10
	v_or_b32_e32 v30, s53, v3
	v_or_b32_e32 v32, s61, v10
	v_or_b32_e32 v34, s62, v3
	v_or_b32_e32 v36, s63, v10
	v_or_b32_e32 v38, s64, v3
	v_or_b32_e32 v40, s65, v10
	v_or_b32_e32 v42, s68, v3
	v_or_b32_e32 v44, s69, v10
	v_ashrrev_i32_e32 v15, 31, v14
	v_lshlrev_b64 v[16:17], 13, v[16:17]
	v_ashrrev_i32_e32 v21, 31, v20
	v_ashrrev_i32_e32 v19, 31, v18
	v_ashrrev_i32_e32 v25, 31, v24
	v_ashrrev_i32_e32 v23, 31, v22
	v_ashrrev_i32_e32 v29, 31, v28
	v_ashrrev_i32_e32 v27, 31, v26
	v_ashrrev_i32_e32 v33, 31, v32
	v_ashrrev_i32_e32 v31, 31, v30
	v_ashrrev_i32_e32 v37, 31, v36
	v_ashrrev_i32_e32 v35, 31, v34
	v_ashrrev_i32_e32 v41, 31, v40
	v_ashrrev_i32_e32 v39, 31, v38
	v_ashrrev_i32_e32 v45, 31, v44
	v_ashrrev_i32_e32 v43, 31, v42
	v_lshlrev_b64 v[14:15], 13, v[14:15]
	v_lshl_add_u64 v[16:17], v[8:9], 0, v[16:17]
	v_lshlrev_b64 v[18:19], 13, v[18:19]
	v_lshlrev_b64 v[20:21], 13, v[20:21]
	v_lshlrev_b64 v[22:23], 13, v[22:23]
	v_lshlrev_b64 v[24:25], 13, v[24:25]
	v_lshlrev_b64 v[26:27], 13, v[26:27]
	v_lshlrev_b64 v[28:29], 13, v[28:29]
	v_lshlrev_b64 v[30:31], 13, v[30:31]
	v_lshlrev_b64 v[32:33], 13, v[32:33]
	v_lshlrev_b64 v[34:35], 13, v[34:35]
	v_lshlrev_b64 v[36:37], 13, v[36:37]
	v_lshlrev_b64 v[38:39], 13, v[38:39]
	v_lshlrev_b64 v[40:41], 13, v[40:41]
	v_lshlrev_b64 v[42:43], 13, v[42:43]
	v_lshlrev_b64 v[44:45], 13, v[44:45]
	v_lshl_add_u64 v[14:15], v[8:9], 0, v[14:15]
	v_lshl_add_u64 v[20:21], v[8:9], 0, v[20:21]
	v_lshl_add_u64 v[18:19], v[8:9], 0, v[18:19]
	v_lshl_add_u64 v[24:25], v[8:9], 0, v[24:25]
	v_lshl_add_u64 v[22:23], v[8:9], 0, v[22:23]
	v_lshl_add_u64 v[28:29], v[8:9], 0, v[28:29]
	v_lshl_add_u64 v[26:27], v[8:9], 0, v[26:27]
	v_lshl_add_u64 v[32:33], v[8:9], 0, v[32:33]
	v_lshl_add_u64 v[30:31], v[8:9], 0, v[30:31]
	v_lshl_add_u64 v[36:37], v[8:9], 0, v[36:37]
	v_lshl_add_u64 v[34:35], v[8:9], 0, v[34:35]
	v_lshl_add_u64 v[40:41], v[8:9], 0, v[40:41]
	v_lshl_add_u64 v[38:39], v[8:9], 0, v[38:39]
	v_lshl_add_u64 v[44:45], v[8:9], 0, v[44:45]
	v_lshl_add_u64 v[42:43], v[8:9], 0, v[42:43]
	global_load_dword v46, v[16:17], off nt
	global_load_dword v47, v[14:15], off nt
	global_load_dword v48, v[20:21], off nt
	global_load_dword v49, v[18:19], off nt
	global_load_dword v50, v[24:25], off nt
	global_load_dword v51, v[22:23], off nt
	global_load_dword v52, v[28:29], off nt
	global_load_dword v53, v[26:27], off nt
	global_load_dword v54, v[32:33], off nt
	global_load_dword v55, v[30:31], off nt
	global_load_dword v56, v[36:37], off nt
	global_load_dword v57, v[34:35], off nt
	global_load_dword v58, v[40:41], off nt
	global_load_dword v59, v[38:39], off nt
	global_load_dword v60, v[44:45], off nt
	global_load_dword v61, v[42:43], off nt
	v_or_b32_e32 v16, s9, v1
	v_or_b32_e32 v14, s23, v0
	s_add_i32 s7, s7, 16
	s_add_i32 s5, s5, 16
	s_add_i32 s8, s8, -16
	v_mad_u64_u32 v[14:15], s[34:35], v14, s60, v[4:5]
	v_mad_u64_u32 v[16:17], s[34:35], v16, s60, v[4:5]
	v_or_b32_e32 v15, s24, v1
	v_or_b32_e32 v17, s25, v0
	v_or_b32_e32 v24, s26, v1
	v_or_b32_e32 v22, s27, v0
	v_or_b32_e32 v28, s30, v1
	v_or_b32_e32 v26, s33, v0
	v_or_b32_e32 v32, s53, v1
	v_or_b32_e32 v30, s61, v0
	v_or_b32_e32 v36, s62, v1
	v_or_b32_e32 v34, s63, v0
	v_or_b32_e32 v40, s64, v1
	v_or_b32_e32 v38, s65, v0
	v_or_b32_e32 v44, s68, v1
	v_or_b32_e32 v42, s69, v0
	s_cmp_lg_u32 s8, 0
	v_mad_u64_u32 v[18:19], s[24:25], v17, s60, v[4:5]
	v_mad_u64_u32 v[20:21], s[24:25], v15, s60, v[4:5]
	v_mad_u64_u32 v[22:23], s[24:25], v22, s60, v[4:5]
	v_mad_u64_u32 v[24:25], s[24:25], v24, s60, v[4:5]
	v_mad_u64_u32 v[26:27], s[24:25], v26, s60, v[4:5]
	v_mad_u64_u32 v[28:29], s[24:25], v28, s60, v[4:5]
	v_mad_u64_u32 v[30:31], s[24:25], v30, s60, v[4:5]
	v_mad_u64_u32 v[32:33], s[24:25], v32, s60, v[4:5]
	v_mad_u64_u32 v[34:35], s[24:25], v34, s60, v[4:5]
	v_mad_u64_u32 v[36:37], s[24:25], v36, s60, v[4:5]
	v_mad_u64_u32 v[38:39], s[24:25], v38, s60, v[4:5]
	v_mad_u64_u32 v[40:41], s[24:25], v40, s60, v[4:5]
	v_mad_u64_u32 v[42:43], s[24:25], v42, s60, v[4:5]
	v_mad_u64_u32 v[44:45], s[24:25], v44, s60, v[4:5]
	s_waitcnt vmcnt(15)
	ds_write_b32 v14, v46
	s_waitcnt vmcnt(14)
	ds_write_b32 v16, v47
	s_waitcnt vmcnt(13)
	ds_write_b32 v18, v48
	s_waitcnt vmcnt(12)
	ds_write_b32 v20, v49
	s_waitcnt vmcnt(11)
	ds_write_b32 v22, v50
	s_waitcnt vmcnt(10)
	ds_write_b32 v24, v51
	s_waitcnt vmcnt(9)
	ds_write_b32 v26, v52
	s_waitcnt vmcnt(8)
	ds_write_b32 v28, v53
	s_waitcnt vmcnt(7)
	ds_write_b32 v30, v54
	s_waitcnt vmcnt(6)
	ds_write_b32 v32, v55
	s_waitcnt vmcnt(5)
	ds_write_b32 v34, v56
	s_waitcnt vmcnt(4)
	ds_write_b32 v36, v57
	s_waitcnt vmcnt(3)
	ds_write_b32 v38, v58
	s_waitcnt vmcnt(2)
	ds_write_b32 v40, v59
	s_waitcnt vmcnt(1)
	ds_write_b32 v42, v60
	s_waitcnt vmcnt(0)
	ds_write_b32 v44, v61
	s_cbranch_scc1 .LBB0_422
; #define LAS __attribute__((address_space(3)))
; __device__ __forceinline__ unsigned cvt_pk_bf16(float lo, float hi) { const f32x2 v = (f32x2){lo, hi}; return __builtin_bit_cast(unsigned, __builtin_convertvector(v, bf16v2)); }
; #define LDS_WAIT() asm volatile("s_waitcnt lgkmcnt(0)" ::: "memory")
; __device__ __forceinline__ void transpose_item(const float* W, int ldw, bf16_t* WT, int ldt, int kofs, int nblk, LAS float* scr, int item, int lane) {
;     ...
;     const int c = lane & 7;
; #pragma unroll
;     for (int j = 0; j < 4; ++j) { const int n = (lane >> 3) + 8 * j; const LAS float* s = scr + (8 * c) * 33 + n;
;         u32x4 o; o.x = cvt_pk_bf16(s[0 * 33], s[1 * 33]); o.y = cvt_pk_bf16(s[2 * 33], s[3 * 33]); o.z = cvt_pk_bf16(s[4 * 33], s[5 * 33]); o.w = cvt_pk_bf16(s[6 * 33], s[7 * 33]);
;         *(u32x4*)(WT + (size_t)(n0 + n) * ldt + kofs + k0 + 8 * c) = o; }
;     LDS_WAIT(); asm volatile("" ::: "memory");
	s_lshl_b64 s[0:1], s[0:1], 22
	s_waitcnt lgkmcnt(0)
	s_add_u32 s5, s21, s0
	s_addc_u32 s8, s22, s1
	s_ashr_i32 s7, s6, 31
	ds_read2_b32 v[8:9], v7 offset0:33 offset1:41
	ds_read2_b32 v[18:19], v7 offset1:8
	ds_read2_b32 v[20:21], v7 offset0:66 offset1:74
	ds_read2_b32 v[22:23], v7 offset0:99 offset1:107
	ds_read2_b32 v[24:25], v7 offset0:132 offset1:140
	ds_read2_b32 v[26:27], v7 offset0:165 offset1:173
	ds_read2_b32 v[28:29], v7 offset0:198 offset1:206
	ds_read2_b32 v[30:31], v7 offset0:231 offset1:239
	s_lshl_b64 s[0:1], s[6:7], 1
	s_add_u32 s0, s5, s0
	v_or_b32_e32 v34, s4, v5
	s_addc_u32 s1, s8, s1
	v_lshlrev_b32_e32 v156, 1, v6
	v_ashrrev_i32_e32 v35, 31, v34
	v_lshl_add_u64 v[32:33], s[0:1], 0, v[156:157]
	v_lshlrev_b64 v[34:35], 11, v[34:35]
	s_waitcnt lgkmcnt(6)
	v_cvt_pk_bf16_f32 v14, v18, v8
	s_waitcnt lgkmcnt(4)
	v_cvt_pk_bf16_f32 v15, v20, v22
	s_waitcnt lgkmcnt(2)
	v_cvt_pk_bf16_f32 v16, v24, v26
	s_waitcnt lgkmcnt(0)
	v_cvt_pk_bf16_f32 v17, v28, v30
	v_lshl_add_u64 v[34:35], v[32:33], 0, v[34:35]
	v_or_b32_e32 v8, s4, v11
	global_store_dwordx4 v[34:35], v[14:17], off
	s_nop 1
	v_cvt_pk_bf16_f32 v14, v19, v9
	v_ashrrev_i32_e32 v9, 31, v8
	v_cvt_pk_bf16_f32 v15, v21, v23
	v_cvt_pk_bf16_f32 v16, v25, v27
	v_cvt_pk_bf16_f32 v17, v29, v31
	v_lshlrev_b64 v[8:9], 11, v[8:9]
	ds_read2_b32 v[18:19], v7 offset0:49 offset1:57
	ds_read2_b32 v[20:21], v7 offset0:16 offset1:24
	ds_read2_b32 v[22:23], v7 offset0:82 offset1:90
	ds_read2_b32 v[24:25], v7 offset0:115 offset1:123
	ds_read2_b32 v[26:27], v7 offset0:148 offset1:156
	ds_read2_b32 v[28:29], v7 offset0:181 offset1:189
	ds_read2_b32 v[30:31], v7 offset0:214 offset1:222
	ds_read2_b32 v[34:35], v7 offset0:247 offset1:255
	v_lshl_add_u64 v[8:9], v[32:33], 0, v[8:9]
	global_store_dwordx4 v[8:9], v[14:17], off
	v_or_b32_e32 v8, s4, v12
	v_ashrrev_i32_e32 v9, 31, v8
	v_lshlrev_b64 v[8:9], 11, v[8:9]
	s_waitcnt lgkmcnt(6)
	v_cvt_pk_bf16_f32 v14, v20, v18
	s_waitcnt lgkmcnt(4)
	v_cvt_pk_bf16_f32 v15, v22, v24
	s_waitcnt lgkmcnt(2)
	v_cvt_pk_bf16_f32 v16, v26, v28
	s_waitcnt lgkmcnt(0)
	v_cvt_pk_bf16_f32 v17, v30, v34
	v_lshl_add_u64 v[8:9], v[32:33], 0, v[8:9]
	global_store_dwordx4 v[8:9], v[14:17], off
	v_or_b32_e32 v8, s4, v13
	v_ashrrev_i32_e32 v9, 31, v8
	v_lshlrev_b64 v[8:9], 11, v[8:9]
	v_cvt_pk_bf16_f32 v14, v21, v19
	v_cvt_pk_bf16_f32 v15, v23, v25
	v_cvt_pk_bf16_f32 v16, v27, v29
	v_cvt_pk_bf16_f32 v17, v31, v35
	v_lshl_add_u64 v[8:9], v[32:33], 0, v[8:9]
	global_store_dwordx4 v[8:9], v[14:17], off
	s_waitcnt lgkmcnt(0)
	s_branch .LBB0_403
